# hand-rewritten GLA scan phase (deeper prefetch, uniform waves) + nt epilogue stores in in-proj GEMM
# speedup vs baseline: 1.0093x; 1.0093x over previous
;     __device__ __forceinline__ void operator()(const f32x4 (&acc)[2][2][4][2], const pg8::Unit& u, int wr, int wc, int fr, int fq) const {
;     ...
;         const bool tr = (pn >= 8 && pn < 12) || (pn >= 24 && pn < 32);
;         unsigned char* base; int colt, ld;
;         if (pn < 24) { base = ws + WS_AQ + (size_t)(pn >> 2) * SZ1; colt = (pn & 3) * 256; ld = 1024; }
;         else { base = ws + WS_BVT + (size_t)((pn - 24) >> 3) * SZ2; colt = ((pn - 24) & 7) * 256; ld = 2048; }
;         if (tr) {
;             bf16_t* VO = (bf16_t*)base; const bool isb = pn >= 24;
;             bf16_t* T = (bf16_t*)(lds_epi + (wr * 4 + wc) * 2048);
;             const int lane = fq * 16 + fr, col = lane & 31, half = lane >> 5;
; #pragma unroll
;             for (int ai = 0; ai < 2; ++ai)
; #pragma unroll
;                 for (int m = 0; m < 4; ++m)
; #pragma unroll
;                     for (int bj = 0; bj < 2; ++bj) {
; #pragma unroll
;                         for (int n = 0; n < 2; ++n) { const f32x4 v = acc[ai][bj][m][n]; const unsigned w0 = pk2(v[0], v[1]), w1 = pk2(v[2], v[3]);
;                             bf16_t* p = T + (8 * fq + 4 * n) * 24 + fr;
;                             p[0] = (bf16_t)(w0 & 0xffffu); p[24] = (bf16_t)(w0 >> 16); p[48] = (bf16_t)(w1 & 0xffffu); p[72] = (bf16_t)(w1 >> 16); }
;                         asm volatile("s_waitcnt lgkmcnt(0)" ::: "memory");
;                         const u32x4 w = *(const u32x4*)(T + col * 24 + half * 8);
;                         asm volatile("s_waitcnt lgkmcnt(0)" ::: "memory");
;                         const int dvg = colt + bj * 128 + wc * 32 + col;
;                         if (isb) { const size_t gc = (size_t)u.pm * 4 + ai * 2 + wr;
;                             *(u32x4*)(VO + ((((gc * 4 + (dvg >> 9)) * 16 + ((dvg >> 5) & 15)) * 4 + m) * 64 + half * 32 + col) * 8) = w; }
;                         else *(u32x4*)(VO + (size_t)dvg * MR + (size_t)(u.pm * 256 + ai * 128 + wr * 64 + m * 16 + half * 8)) = w;
;                     }
;         } else {
;             bf16_t* O = (bf16_t*)base; const int col0 = colt + wc * 32 + 8 * fq;
; #pragma unroll
;             for (int ai = 0; ai < 2; ++ai)
; #pragma unroll
;                 for (int m = 0; m < 4; ++m) { bf16_t* rowp = O + (size_t)(row0 + ai * 128 + m * 16) * ld + col0;
; #pragma unroll
.LBB0_197:
	s_and_b32 s7, s6, -4
	s_cmp_lg_u32 s7, 8
	s_cselect_b64 s[44:45], -1, 0
	s_and_b32 s7, s6, -8
	s_cmp_lg_u32 s7, 24
	s_cselect_b64 s[56:57], -1, 0
	s_and_b64 s[56:57], s[44:45], s[56:57]
	s_lshl_b32 s7, s6, 8
	s_and_b32 s10, s3, s7
	s_mov_b64 s[44:45], -1
	s_and_b64 vcc, exec, s[56:57]
	v_cvt_pk_bf16_f32 v130, v60, v61
	v_cvt_pk_bf16_f32 v131, v62, v63
	v_cvt_pk_bf16_f32 v132, v56, v57
	v_cvt_pk_bf16_f32 v133, v58, v59
	v_cvt_pk_bf16_f32 v126, v126, v127
	v_cvt_pk_bf16_f32 v127, v128, v129
	v_cvt_pk_bf16_f32 v128, v122, v123
	v_cvt_pk_bf16_f32 v129, v124, v125
	v_cvt_pk_bf16_f32 v122, v52, v53
	v_cvt_pk_bf16_f32 v123, v54, v55
	v_cvt_pk_bf16_f32 v124, v48, v49
	v_cvt_pk_bf16_f32 v125, v50, v51
	v_cvt_pk_bf16_f32 v118, v118, v119
	v_cvt_pk_bf16_f32 v119, v120, v121
	v_cvt_pk_bf16_f32 v120, v114, v115
	v_cvt_pk_bf16_f32 v121, v116, v117
	v_cvt_pk_bf16_f32 v114, v44, v45
	v_cvt_pk_bf16_f32 v115, v46, v47
	v_cvt_pk_bf16_f32 v116, v40, v41
	v_cvt_pk_bf16_f32 v117, v42, v43
	v_cvt_pk_bf16_f32 v110, v110, v111
	v_cvt_pk_bf16_f32 v111, v112, v113
	v_cvt_pk_bf16_f32 v112, v106, v107
	v_cvt_pk_bf16_f32 v113, v108, v109
	v_cvt_pk_bf16_f32 v106, v36, v37
	v_cvt_pk_bf16_f32 v107, v38, v39
	v_cvt_pk_bf16_f32 v108, v32, v33
	v_cvt_pk_bf16_f32 v109, v34, v35
	v_cvt_pk_bf16_f32 v102, v102, v103
	v_cvt_pk_bf16_f32 v103, v104, v105
	v_cvt_pk_bf16_f32 v104, v98, v99
	v_cvt_pk_bf16_f32 v105, v100, v101
	v_cvt_pk_bf16_f32 v98, v28, v29
	v_cvt_pk_bf16_f32 v99, v30, v31
	v_cvt_pk_bf16_f32 v100, v24, v25
	v_cvt_pk_bf16_f32 v101, v26, v27
	v_cvt_pk_bf16_f32 v94, v94, v95
	v_cvt_pk_bf16_f32 v95, v96, v97
	v_cvt_pk_bf16_f32 v96, v90, v91
	v_cvt_pk_bf16_f32 v97, v92, v93
	v_cvt_pk_bf16_f32 v90, v20, v21
	v_cvt_pk_bf16_f32 v91, v22, v23
	v_cvt_pk_bf16_f32 v92, v16, v17
	v_cvt_pk_bf16_f32 v93, v18, v19
	v_cvt_pk_bf16_f32 v86, v86, v87
	v_cvt_pk_bf16_f32 v87, v88, v89
	v_cvt_pk_bf16_f32 v88, v82, v83
	v_cvt_pk_bf16_f32 v89, v84, v85
	v_cvt_pk_bf16_f32 v82, v12, v13
	v_cvt_pk_bf16_f32 v83, v14, v15
	v_cvt_pk_bf16_f32 v84, v8, v9
	v_cvt_pk_bf16_f32 v85, v10, v11
	v_cvt_pk_bf16_f32 v78, v78, v79
	v_cvt_pk_bf16_f32 v79, v80, v81
	v_cvt_pk_bf16_f32 v80, v70, v71
	v_cvt_pk_bf16_f32 v81, v72, v73
	v_cvt_pk_bf16_f32 v70, v4, v5
	v_cvt_pk_bf16_f32 v71, v6, v7
	v_cvt_pk_bf16_f32 v72, v0, v1
	v_cvt_pk_bf16_f32 v73, v2, v3
	v_cvt_pk_bf16_f32 v64, v74, v75
	v_cvt_pk_bf16_f32 v65, v76, v77
	v_cvt_pk_bf16_f32 v66, v66, v67
	v_cvt_pk_bf16_f32 v67, v68, v69
	s_cbranch_vccz .LBB0_199
	v_or_b32_e32 v68, s10, v162
	v_lshlrev_b32_e32 v142, 1, v68
	v_lshl_add_u64 v[68:69], s[40:41], 0, v[142:143]
	v_mad_i64_i32 v[74:75], s[44:45], s42, v156, 0
	v_lshl_add_u64 v[74:75], v[74:75], 1, v[68:69]
	global_store_dwordx4 v[74:75], v[130:133], off nt
	global_store_dwordx4 v[74:75], v[126:129], off offset:256 nt
	v_or_b32_e32 v74, 16, v156
	v_mad_i64_i32 v[74:75], s[44:45], s42, v74, 0
	v_lshl_add_u64 v[74:75], v[74:75], 1, v[68:69]
	global_store_dwordx4 v[74:75], v[122:125], off nt
	global_store_dwordx4 v[74:75], v[118:121], off offset:256 nt
	v_or_b32_e32 v74, 32, v156
	v_mad_i64_i32 v[74:75], s[44:45], s42, v74, 0
	v_lshl_add_u64 v[74:75], v[74:75], 1, v[68:69]
	global_store_dwordx4 v[74:75], v[114:117], off nt
	global_store_dwordx4 v[74:75], v[110:113], off offset:256 nt
	v_or_b32_e32 v74, 48, v156
	v_mad_i64_i32 v[74:75], s[44:45], s42, v74, 0
	v_lshl_add_u64 v[74:75], v[74:75], 1, v[68:69]
	global_store_dwordx4 v[74:75], v[106:109], off nt
	global_store_dwordx4 v[74:75], v[102:105], off offset:256 nt
	v_add_u32_e32 v74, 0x80, v156
	v_mad_i64_i32 v[74:75], s[44:45], s42, v74, 0
	v_lshl_add_u64 v[74:75], v[74:75], 1, v[68:69]
	global_store_dwordx4 v[74:75], v[98:101], off nt
	global_store_dwordx4 v[74:75], v[94:97], off offset:256 nt
	v_add_u32_e32 v74, 0x90, v156
	v_mad_i64_i32 v[74:75], s[44:45], s42, v74, 0
	v_lshl_add_u64 v[74:75], v[74:75], 1, v[68:69]
	global_store_dwordx4 v[74:75], v[90:93], off nt
	global_store_dwordx4 v[74:75], v[86:89], off offset:256 nt
	v_add_u32_e32 v74, 0xa0, v156
	v_mad_i64_i32 v[74:75], s[44:45], s42, v74, 0
	v_lshl_add_u64 v[74:75], v[74:75], 1, v[68:69]
	global_store_dwordx4 v[74:75], v[82:85], off nt
	global_store_dwordx4 v[74:75], v[78:81], off offset:256 nt
	v_add_u32_e32 v74, 0xb0, v156
	v_mad_i64_i32 v[74:75], s[42:43], s42, v74, 0
	v_lshl_add_u64 v[68:69], v[74:75], 1, v[68:69]
	global_store_dwordx4 v[68:69], v[70:73], off nt
	global_store_dwordx4 v[68:69], v[64:67], off offset:256 nt
	s_mov_b64 s[44:45], 0
.LBB0_199:
	s_andn2_b64 vcc, exec, s[44:45]
	s_cbranch_vccnz .LBB0_264
	ds_write_b16 v166, v130
	ds_write_b16_d16_hi v166, v130 offset:48
	ds_write_b16 v166, v131 offset:96
	ds_write_b16_d16_hi v166, v131 offset:144
	ds_write_b16 v166, v132 offset:192
	ds_write_b16_d16_hi v166, v132 offset:240
	ds_write_b16 v166, v133 offset:288
	ds_write_b16_d16_hi v166, v133 offset:336
	s_waitcnt lgkmcnt(0)
	ds_read_b128 v[74:77], v164
	s_cmp_lt_u32 s6, 24
	s_cselect_b64 s[42:43], -1, 0
	s_or_b32 s3, s10, s66
	s_waitcnt lgkmcnt(0)
	v_or_b32_e32 v69, s3, v163
	v_add_u32_e32 v68, s1, v165
	s_mov_b64 s[6:7], -1
	s_and_b64 vcc, exec, s[42:43]
	v_mul_u32_u24_e32 v130, 0x8200, v69
	v_ashrrev_i32_e32 v69, 31, v68
	s_cbranch_vccz .LBB0_202
	v_lshlrev_b32_e32 v142, 1, v130
	v_lshl_add_u64 v[132:133], s[40:41], 0, v[142:143]
	v_lshl_add_u64 v[132:133], v[68:69], 1, v[132:133]
	s_waitcnt lgkmcnt(0)
	global_store_dwordx4 v[132:133], v[74:77], off nt
	s_mov_b64 s[6:7], 0
; __device__ __forceinline__ unsigned pk2(float lo, float hi) { const f32x2 v = {lo, hi}; const bf16x2_t b = __builtin_convertvector(v, bf16x2_t); return __builtin_bit_cast(unsigned, b); }
;     __device__ __forceinline__ void operator()(const f32x4 (&acc)[2][2][4][2], const pg8::Unit& u, int wr, int wc, int fr, int fq) const {
;     ...
;                     for (int bj = 0; bj < 2; ++bj) {
; #pragma unroll
;                         for (int n = 0; n < 2; ++n) { const f32x4 v = acc[ai][bj][m][n]; const unsigned w0 = pk2(v[0], v[1]), w1 = pk2(v[2], v[3]);
;                             bf16_t* p = T + (8 * fq + 4 * n) * 24 + fr;
;                             p[0] = (bf16_t)(w0 & 0xffffu); p[24] = (bf16_t)(w0 >> 16); p[48] = (bf16_t)(w1 & 0xffffu); p[72] = (bf16_t)(w1 >> 16); }
;                         asm volatile("s_waitcnt lgkmcnt(0)" ::: "memory");
;                         const u32x4 w = *(const u32x4*)(T + col * 24 + half * 8);
;                         asm volatile("s_waitcnt lgkmcnt(0)" ::: "memory");
;                         const int dvg = colt + bj * 128 + wc * 32 + col;
;                         if (isb) { const size_t gc = (size_t)u.pm * 4 + ai * 2 + wr;
;                             *(u32x4*)(VO + ((((gc * 4 + (dvg >> 9)) * 16 + ((dvg >> 5) & 15)) * 4 + m) * 64 + half * 32 + col) * 8) = w; }
;                         else *(u32x4*)(VO + (size_t)dvg * MR + (size_t)(u.pm * 256 + ai * 128 + wr * 64 + m * 16 + half * 8)) = w;
;                     }
.LBB0_202:
	s_lshr_b32 s10, s10, 5
	s_andn2_b64 vcc, exec, s[6:7]
	s_and_b32 s10, s10, 48
	s_cbranch_vccnz .LBB0_204
	s_ashr_i32 s13, s12, 31
	s_lshl_b64 s[6:7], s[12:13], 8
	s_add_u32 s6, s6, s55
	s_addc_u32 s7, s7, 0
	s_lshr_b32 s13, s3, 5
	s_and_b32 s13, s13, 11
	s_or_b32 s6, s6, s13
	s_or_b64 s[6:7], s[6:7], s[10:11]
	s_lshl_b64 s[6:7], s[6:7], 12
	s_add_u32 s6, s40, s6
	s_addc_u32 s7, s41, s7
	v_lshl_add_u64 v[132:133], s[6:7], 0, v[144:145]
	s_waitcnt lgkmcnt(0)
	global_store_dwordx4 v[132:133], v[74:77], off nt
.LBB0_204:
	ds_write_b16 v166, v126
	ds_write_b16_d16_hi v166, v126 offset:48
	ds_write_b16 v166, v127 offset:96
	ds_write_b16_d16_hi v166, v127 offset:144
	ds_write_b16 v166, v128 offset:192
	ds_write_b16_d16_hi v166, v128 offset:240
	ds_write_b16 v166, v129 offset:288
	ds_write_b16_d16_hi v166, v129 offset:336
	s_waitcnt lgkmcnt(0)
	s_waitcnt lgkmcnt(0)
	ds_read_b128 v[74:77], v164
	s_waitcnt lgkmcnt(0)
	s_or_b32 s31, s3, 0x80
	v_cndmask_b32_e64 v126, 0, 1, s[42:43]
	v_cmp_ne_u32_e64 s[6:7], 1, v126
	v_or_b32_e32 v126, s31, v163
	s_mov_b64 s[44:45], -1
	s_andn2_b64 vcc, exec, s[42:43]
	v_mul_u32_u24_e32 v126, 0x8200, v126
	s_cbranch_vccnz .LBB0_206
	v_lshlrev_b32_e32 v142, 1, v126
	v_lshl_add_u64 v[128:129], s[40:41], 0, v[142:143]
	v_lshl_add_u64 v[68:69], v[68:69], 1, v[128:129]
	s_mov_b64 s[44:45], 0
	s_waitcnt lgkmcnt(0)
	global_store_dwordx4 v[68:69], v[74:77], off nt
.LBB0_206:
	s_andn2_b64 vcc, exec, s[44:45]
	s_cbranch_vccnz .LBB0_208
	s_ashr_i32 s13, s12, 31
	s_lshl_b64 s[42:43], s[12:13], 8
	s_add_u32 s13, s42, s55
	s_addc_u32 s43, s43, 0
	s_bfe_u32 s33, s31, 0x40005
	s_or_b32 s42, s13, s33
	s_or_b64 s[42:43], s[42:43], s[10:11]
	s_lshl_b64 s[42:43], s[42:43], 12
	s_add_u32 s42, s40, s42
	s_addc_u32 s43, s41, s43
	v_lshl_add_u64 v[68:69], s[42:43], 0, v[144:145]
	s_waitcnt lgkmcnt(0)
	global_store_dwordx4 v[68:69], v[74:77], off nt
.LBB0_208:
	ds_write_b16 v166, v122
	ds_write_b16_d16_hi v166, v122 offset:48
	ds_write_b16 v166, v123 offset:96
	ds_write_b16_d16_hi v166, v123 offset:144
	ds_write_b16 v166, v124 offset:192
	ds_write_b16_d16_hi v166, v124 offset:240
	ds_write_b16 v166, v125 offset:288
	ds_write_b16_d16_hi v166, v125 offset:336
	s_waitcnt lgkmcnt(0)
	s_waitcnt lgkmcnt(0)
	ds_read_b128 v[74:77], v164
	s_waitcnt lgkmcnt(0)
	v_add_u32_e32 v68, s1, v167
	s_mov_b64 s[42:43], -1
	s_and_b64 vcc, exec, s[6:7]
	v_ashrrev_i32_e32 v69, 31, v68
	s_cbranch_vccnz .LBB0_210
	v_lshlrev_b32_e32 v142, 1, v130
	v_lshl_add_u64 v[122:123], s[40:41], 0, v[142:143]
	v_lshl_add_u64 v[122:123], v[68:69], 1, v[122:123]
	s_mov_b64 s[42:43], 0
	s_waitcnt lgkmcnt(0)
	global_store_dwordx4 v[122:123], v[74:77], off nt
.LBB0_210:
	s_andn2_b64 vcc, exec, s[42:43]
	s_cbranch_vccnz .LBB0_212
	s_ashr_i32 s13, s12, 31
	s_lshl_b64 s[42:43], s[12:13], 8
	s_add_u32 s13, s42, s55
	s_addc_u32 s43, s43, 0
	s_lshr_b32 s33, s3, 5
	s_and_b32 s33, s33, 11
	s_or_b32 s42, s13, s33
	s_or_b64 s[42:43], s[42:43], s[10:11]
	s_lshl_b64 s[42:43], s[42:43], 12
	s_add_u32 s42, s40, s42
	s_addc_u32 s43, s41, s43
	v_lshl_add_u64 v[122:123], s[42:43], 0, v[144:145]
	s_waitcnt lgkmcnt(0)
	global_store_dwordx4 v[122:123], v[74:77], off offset:1024 nt
.LBB0_212:
	ds_write_b16 v166, v118
	ds_write_b16_d16_hi v166, v118 offset:48
	ds_write_b16 v166, v119 offset:96
	ds_write_b16_d16_hi v166, v119 offset:144
	ds_write_b16 v166, v120 offset:192
	ds_write_b16_d16_hi v166, v120 offset:240
	ds_write_b16 v166, v121 offset:288
	ds_write_b16_d16_hi v166, v121 offset:336
	s_waitcnt lgkmcnt(0)
	s_waitcnt lgkmcnt(0)
	ds_read_b128 v[74:77], v164
	s_waitcnt lgkmcnt(0)
	s_and_b64 vcc, exec, s[6:7]
	s_mov_b64 s[42:43], -1
	s_cbranch_vccnz .LBB0_214
	v_lshlrev_b32_e32 v142, 1, v126
	v_lshl_add_u64 v[118:119], s[40:41], 0, v[142:143]
	v_lshl_add_u64 v[68:69], v[68:69], 1, v[118:119]
	s_mov_b64 s[42:43], 0
	s_waitcnt lgkmcnt(0)
	global_store_dwordx4 v[68:69], v[74:77], off nt
.LBB0_214:
	s_andn2_b64 vcc, exec, s[42:43]
	s_cbranch_vccnz .LBB0_216
	s_ashr_i32 s13, s12, 31
	s_lshl_b64 s[42:43], s[12:13], 8
	s_add_u32 s13, s42, s55
	s_addc_u32 s43, s43, 0
	s_bfe_u32 s33, s31, 0x40005
	s_or_b32 s42, s13, s33
	s_or_b64 s[42:43], s[42:43], s[10:11]
	s_lshl_b64 s[42:43], s[42:43], 12
	s_add_u32 s42, s40, s42
	s_addc_u32 s43, s41, s43
	v_lshl_add_u64 v[68:69], s[42:43], 0, v[144:145]
	s_waitcnt lgkmcnt(0)
	global_store_dwordx4 v[68:69], v[74:77], off offset:1024 nt
.LBB0_216:
	ds_write_b16 v166, v114
	ds_write_b16_d16_hi v166, v114 offset:48
	ds_write_b16 v166, v115 offset:96
	ds_write_b16_d16_hi v166, v115 offset:144
	ds_write_b16 v166, v116 offset:192
	ds_write_b16_d16_hi v166, v116 offset:240
	ds_write_b16 v166, v117 offset:288
	ds_write_b16_d16_hi v166, v117 offset:336
	s_waitcnt lgkmcnt(0)
	s_waitcnt lgkmcnt(0)
	ds_read_b128 v[74:77], v164
	s_waitcnt lgkmcnt(0)
	v_add_u32_e32 v68, s1, v168
	s_mov_b64 s[42:43], -1
	s_and_b64 vcc, exec, s[6:7]
	v_ashrrev_i32_e32 v69, 31, v68
	s_cbranch_vccnz .LBB0_218
	v_lshlrev_b32_e32 v142, 1, v130
	v_lshl_add_u64 v[114:115], s[40:41], 0, v[142:143]
	v_lshl_add_u64 v[114:115], v[68:69], 1, v[114:115]
	s_mov_b64 s[42:43], 0
	s_waitcnt lgkmcnt(0)
	global_store_dwordx4 v[114:115], v[74:77], off nt
.LBB0_218:
	s_andn2_b64 vcc, exec, s[42:43]
	s_cbranch_vccnz .LBB0_220
	s_ashr_i32 s13, s12, 31
	s_lshl_b64 s[42:43], s[12:13], 8
	s_add_u32 s13, s42, s55
	s_addc_u32 s43, s43, 0
	s_lshr_b32 s33, s3, 5
	s_and_b32 s33, s33, 11
	s_or_b32 s42, s13, s33
	s_or_b64 s[42:43], s[42:43], s[10:11]
	s_lshl_b64 s[42:43], s[42:43], 12
	s_add_u32 s42, s40, s42
	s_addc_u32 s43, s41, s43
	v_lshl_add_u64 v[114:115], s[42:43], 0, v[144:145]
	s_waitcnt lgkmcnt(0)
	global_store_dwordx4 v[114:115], v[74:77], off offset:2048 nt
; __device__ __forceinline__ unsigned pk2(float lo, float hi) { const f32x2 v = {lo, hi}; const bf16x2_t b = __builtin_convertvector(v, bf16x2_t); return __builtin_bit_cast(unsigned, b); }
;     __device__ __forceinline__ void operator()(const f32x4 (&acc)[2][2][4][2], const pg8::Unit& u, int wr, int wc, int fr, int fq) const {
;     ...
;                     for (int bj = 0; bj < 2; ++bj) {
; #pragma unroll
;                         for (int n = 0; n < 2; ++n) { const f32x4 v = acc[ai][bj][m][n]; const unsigned w0 = pk2(v[0], v[1]), w1 = pk2(v[2], v[3]);
;                             bf16_t* p = T + (8 * fq + 4 * n) * 24 + fr;
;                             p[0] = (bf16_t)(w0 & 0xffffu); p[24] = (bf16_t)(w0 >> 16); p[48] = (bf16_t)(w1 & 0xffffu); p[72] = (bf16_t)(w1 >> 16); }
;                         asm volatile("s_waitcnt lgkmcnt(0)" ::: "memory");
;                         const u32x4 w = *(const u32x4*)(T + col * 24 + half * 8);
;                         asm volatile("s_waitcnt lgkmcnt(0)" ::: "memory");
;                         const int dvg = colt + bj * 128 + wc * 32 + col;
;                         if (isb) { const size_t gc = (size_t)u.pm * 4 + ai * 2 + wr;
;                             *(u32x4*)(VO + ((((gc * 4 + (dvg >> 9)) * 16 + ((dvg >> 5) & 15)) * 4 + m) * 64 + half * 32 + col) * 8) = w; }
;                         else *(u32x4*)(VO + (size_t)dvg * MR + (size_t)(u.pm * 256 + ai * 128 + wr * 64 + m * 16 + half * 8)) = w;
;                     }
.LBB0_220:
	ds_write_b16 v166, v110
	ds_write_b16_d16_hi v166, v110 offset:48
	ds_write_b16 v166, v111 offset:96
	ds_write_b16_d16_hi v166, v111 offset:144
	ds_write_b16 v166, v112 offset:192
	ds_write_b16_d16_hi v166, v112 offset:240
	ds_write_b16 v166, v113 offset:288
	ds_write_b16_d16_hi v166, v113 offset:336
	s_waitcnt lgkmcnt(0)
	s_waitcnt lgkmcnt(0)
	ds_read_b128 v[74:77], v164
	s_waitcnt lgkmcnt(0)
	s_and_b64 vcc, exec, s[6:7]
	s_mov_b64 s[42:43], -1
	s_cbranch_vccnz .LBB0_222
	v_lshlrev_b32_e32 v142, 1, v126
	v_lshl_add_u64 v[110:111], s[40:41], 0, v[142:143]
	v_lshl_add_u64 v[68:69], v[68:69], 1, v[110:111]
	s_mov_b64 s[42:43], 0
	s_waitcnt lgkmcnt(0)
	global_store_dwordx4 v[68:69], v[74:77], off nt
.LBB0_222:
	s_andn2_b64 vcc, exec, s[42:43]
	s_cbranch_vccnz .LBB0_224
	s_ashr_i32 s13, s12, 31
	s_lshl_b64 s[42:43], s[12:13], 8
	s_add_u32 s13, s42, s55
	s_addc_u32 s43, s43, 0
	s_bfe_u32 s33, s31, 0x40005
	s_or_b32 s42, s13, s33
	s_or_b64 s[42:43], s[42:43], s[10:11]
	s_lshl_b64 s[42:43], s[42:43], 12
	s_add_u32 s42, s40, s42
	s_addc_u32 s43, s41, s43
	v_lshl_add_u64 v[68:69], s[42:43], 0, v[144:145]
	s_waitcnt lgkmcnt(0)
	global_store_dwordx4 v[68:69], v[74:77], off offset:2048 nt
.LBB0_224:
	ds_write_b16 v166, v106
	ds_write_b16_d16_hi v166, v106 offset:48
	ds_write_b16 v166, v107 offset:96
	ds_write_b16_d16_hi v166, v107 offset:144
	ds_write_b16 v166, v108 offset:192
	ds_write_b16_d16_hi v166, v108 offset:240
	ds_write_b16 v166, v109 offset:288
	ds_write_b16_d16_hi v166, v109 offset:336
	s_waitcnt lgkmcnt(0)
	s_waitcnt lgkmcnt(0)
	ds_read_b128 v[74:77], v164
	s_waitcnt lgkmcnt(0)
	v_add_u32_e32 v68, s1, v169
	s_mov_b64 s[42:43], -1
	s_and_b64 vcc, exec, s[6:7]
	v_ashrrev_i32_e32 v69, 31, v68
	s_cbranch_vccnz .LBB0_226
	v_lshlrev_b32_e32 v142, 1, v130
	v_lshl_add_u64 v[106:107], s[40:41], 0, v[142:143]
	v_lshl_add_u64 v[106:107], v[68:69], 1, v[106:107]
	s_mov_b64 s[42:43], 0
	s_waitcnt lgkmcnt(0)
	global_store_dwordx4 v[106:107], v[74:77], off nt
.LBB0_226:
	s_andn2_b64 vcc, exec, s[42:43]
	s_cbranch_vccnz .LBB0_228
	s_ashr_i32 s13, s12, 31
	s_lshl_b64 s[42:43], s[12:13], 8
	s_add_u32 s13, s42, s55
	s_addc_u32 s43, s43, 0
	s_lshr_b32 s33, s3, 5
	s_and_b32 s33, s33, 11
	s_or_b32 s42, s13, s33
	s_or_b64 s[42:43], s[42:43], s[10:11]
	s_lshl_b64 s[42:43], s[42:43], 12
	s_add_u32 s42, s40, s42
	s_addc_u32 s43, s41, s43
	v_lshl_add_u64 v[106:107], s[42:43], 0, v[144:145]
	s_waitcnt lgkmcnt(0)
	global_store_dwordx4 v[106:107], v[74:77], off offset:3072 nt
.LBB0_228:
	ds_write_b16 v166, v102
	ds_write_b16_d16_hi v166, v102 offset:48
	ds_write_b16 v166, v103 offset:96
	ds_write_b16_d16_hi v166, v103 offset:144
	ds_write_b16 v166, v104 offset:192
	ds_write_b16_d16_hi v166, v104 offset:240
	ds_write_b16 v166, v105 offset:288
	ds_write_b16_d16_hi v166, v105 offset:336
	s_waitcnt lgkmcnt(0)
	s_waitcnt lgkmcnt(0)
	ds_read_b128 v[74:77], v164
	s_waitcnt lgkmcnt(0)
	s_and_b64 vcc, exec, s[6:7]
	s_mov_b64 s[42:43], -1
	s_cbranch_vccnz .LBB0_230
	v_lshlrev_b32_e32 v142, 1, v126
	v_lshl_add_u64 v[102:103], s[40:41], 0, v[142:143]
	v_lshl_add_u64 v[68:69], v[68:69], 1, v[102:103]
	s_mov_b64 s[42:43], 0
	s_waitcnt lgkmcnt(0)
	global_store_dwordx4 v[68:69], v[74:77], off nt
.LBB0_230:
	s_andn2_b64 vcc, exec, s[42:43]
	s_cbranch_vccnz .LBB0_232
	s_ashr_i32 s13, s12, 31
	s_lshl_b64 s[42:43], s[12:13], 8
	s_add_u32 s13, s42, s55
	s_addc_u32 s43, s43, 0
	s_bfe_u32 s33, s31, 0x40005
	s_or_b32 s42, s13, s33
	s_or_b64 s[42:43], s[42:43], s[10:11]
	s_lshl_b64 s[42:43], s[42:43], 12
	s_add_u32 s42, s40, s42
	s_addc_u32 s43, s41, s43
	v_lshl_add_u64 v[68:69], s[42:43], 0, v[144:145]
	s_waitcnt lgkmcnt(0)
	global_store_dwordx4 v[68:69], v[74:77], off offset:3072 nt
.LBB0_232:
	ds_write_b16 v166, v98
	ds_write_b16_d16_hi v166, v98 offset:48
	ds_write_b16 v166, v99 offset:96
	ds_write_b16_d16_hi v166, v99 offset:144
	ds_write_b16 v166, v100 offset:192
	ds_write_b16_d16_hi v166, v100 offset:240
	ds_write_b16 v166, v101 offset:288
	ds_write_b16_d16_hi v166, v101 offset:336
	s_waitcnt lgkmcnt(0)
	s_waitcnt lgkmcnt(0)
	ds_read_b128 v[74:77], v164
	s_waitcnt lgkmcnt(0)
	v_add_u32_e32 v68, s1, v170
	s_mov_b64 s[42:43], -1
	s_and_b64 vcc, exec, s[6:7]
	v_ashrrev_i32_e32 v69, 31, v68
	s_cbranch_vccnz .LBB0_234
	v_lshlrev_b32_e32 v142, 1, v130
	v_lshl_add_u64 v[98:99], s[40:41], 0, v[142:143]
	v_lshl_add_u64 v[98:99], v[68:69], 1, v[98:99]
	s_mov_b64 s[42:43], 0
	s_waitcnt lgkmcnt(0)
	global_store_dwordx4 v[98:99], v[74:77], off nt
.LBB0_234:
	s_andn2_b64 vcc, exec, s[42:43]
	s_cbranch_vccnz .LBB0_236
	s_ashr_i32 s13, s12, 31
	s_lshl_b64 s[42:43], s[12:13], 8
	s_add_u32 s13, s42, s79
	s_addc_u32 s43, s43, 0
	s_lshr_b32 s33, s3, 5
	s_and_b32 s33, s33, 11
	s_or_b32 s42, s13, s33
	s_or_b64 s[42:43], s[42:43], s[10:11]
	s_lshl_b64 s[42:43], s[42:43], 12
	s_add_u32 s42, s40, s42
	s_addc_u32 s43, s41, s43
	v_lshl_add_u64 v[98:99], s[42:43], 0, v[144:145]
	s_waitcnt lgkmcnt(0)
	global_store_dwordx4 v[98:99], v[74:77], off nt
.LBB0_236:
	ds_write_b16 v166, v94
	ds_write_b16_d16_hi v166, v94 offset:48
	ds_write_b16 v166, v95 offset:96
	ds_write_b16_d16_hi v166, v95 offset:144
	ds_write_b16 v166, v96 offset:192
	ds_write_b16_d16_hi v166, v96 offset:240
	ds_write_b16 v166, v97 offset:288
	ds_write_b16_d16_hi v166, v97 offset:336
	s_waitcnt lgkmcnt(0)
	s_waitcnt lgkmcnt(0)
	ds_read_b128 v[74:77], v164
	s_waitcnt lgkmcnt(0)
	s_and_b64 vcc, exec, s[6:7]
	s_mov_b64 s[42:43], -1
	s_cbranch_vccnz .LBB0_238
	v_lshlrev_b32_e32 v142, 1, v126
	v_lshl_add_u64 v[94:95], s[40:41], 0, v[142:143]
	v_lshl_add_u64 v[68:69], v[68:69], 1, v[94:95]
	s_mov_b64 s[42:43], 0
	s_waitcnt lgkmcnt(0)
	global_store_dwordx4 v[68:69], v[74:77], off nt
; __device__ __forceinline__ unsigned pk2(float lo, float hi) { const f32x2 v = {lo, hi}; const bf16x2_t b = __builtin_convertvector(v, bf16x2_t); return __builtin_bit_cast(unsigned, b); }
;     __device__ __forceinline__ void operator()(const f32x4 (&acc)[2][2][4][2], const pg8::Unit& u, int wr, int wc, int fr, int fq) const {
;     ...
;                     for (int bj = 0; bj < 2; ++bj) {
; #pragma unroll
;                         for (int n = 0; n < 2; ++n) { const f32x4 v = acc[ai][bj][m][n]; const unsigned w0 = pk2(v[0], v[1]), w1 = pk2(v[2], v[3]);
;                             bf16_t* p = T + (8 * fq + 4 * n) * 24 + fr;
;                             p[0] = (bf16_t)(w0 & 0xffffu); p[24] = (bf16_t)(w0 >> 16); p[48] = (bf16_t)(w1 & 0xffffu); p[72] = (bf16_t)(w1 >> 16); }
;                         asm volatile("s_waitcnt lgkmcnt(0)" ::: "memory");
;                         const u32x4 w = *(const u32x4*)(T + col * 24 + half * 8);
;                         asm volatile("s_waitcnt lgkmcnt(0)" ::: "memory");
;                         const int dvg = colt + bj * 128 + wc * 32 + col;
;                         if (isb) { const size_t gc = (size_t)u.pm * 4 + ai * 2 + wr;
;                             *(u32x4*)(VO + ((((gc * 4 + (dvg >> 9)) * 16 + ((dvg >> 5) & 15)) * 4 + m) * 64 + half * 32 + col) * 8) = w; }
;                         else *(u32x4*)(VO + (size_t)dvg * MR + (size_t)(u.pm * 256 + ai * 128 + wr * 64 + m * 16 + half * 8)) = w;
;                     }
.LBB0_238:
	s_andn2_b64 vcc, exec, s[42:43]
	s_cbranch_vccnz .LBB0_240
	s_ashr_i32 s13, s12, 31
	s_lshl_b64 s[42:43], s[12:13], 8
	s_add_u32 s13, s42, s79
	s_addc_u32 s43, s43, 0
	s_bfe_u32 s33, s31, 0x40005
	s_or_b32 s42, s13, s33
	s_or_b64 s[42:43], s[42:43], s[10:11]
	s_lshl_b64 s[42:43], s[42:43], 12
	s_add_u32 s42, s40, s42
	s_addc_u32 s43, s41, s43
	v_lshl_add_u64 v[68:69], s[42:43], 0, v[144:145]
	s_waitcnt lgkmcnt(0)
	global_store_dwordx4 v[68:69], v[74:77], off nt
.LBB0_240:
	ds_write_b16 v166, v90
	ds_write_b16_d16_hi v166, v90 offset:48
	ds_write_b16 v166, v91 offset:96
	ds_write_b16_d16_hi v166, v91 offset:144
	ds_write_b16 v166, v92 offset:192
	ds_write_b16_d16_hi v166, v92 offset:240
	ds_write_b16 v166, v93 offset:288
	ds_write_b16_d16_hi v166, v93 offset:336
	s_waitcnt lgkmcnt(0)
	s_waitcnt lgkmcnt(0)
	ds_read_b128 v[74:77], v164
	s_waitcnt lgkmcnt(0)
	v_add_u32_e32 v68, s1, v171
	s_mov_b64 s[42:43], -1
	s_and_b64 vcc, exec, s[6:7]
	v_ashrrev_i32_e32 v69, 31, v68
	s_cbranch_vccnz .LBB0_242
	v_lshlrev_b32_e32 v142, 1, v130
	v_lshl_add_u64 v[90:91], s[40:41], 0, v[142:143]
	v_lshl_add_u64 v[90:91], v[68:69], 1, v[90:91]
	s_mov_b64 s[42:43], 0
	s_waitcnt lgkmcnt(0)
	global_store_dwordx4 v[90:91], v[74:77], off nt
.LBB0_242:
	s_andn2_b64 vcc, exec, s[42:43]
	s_cbranch_vccnz .LBB0_244
	s_ashr_i32 s13, s12, 31
	s_lshl_b64 s[42:43], s[12:13], 8
	s_add_u32 s13, s42, s79
	s_addc_u32 s43, s43, 0
	s_lshr_b32 s33, s3, 5
	s_and_b32 s33, s33, 11
	s_or_b32 s42, s13, s33
	s_or_b64 s[42:43], s[42:43], s[10:11]
	s_lshl_b64 s[42:43], s[42:43], 12
	s_add_u32 s42, s40, s42
	s_addc_u32 s43, s41, s43
	v_lshl_add_u64 v[90:91], s[42:43], 0, v[144:145]
	s_waitcnt lgkmcnt(0)
	global_store_dwordx4 v[90:91], v[74:77], off offset:1024 nt
.LBB0_244:
	ds_write_b16 v166, v86
	ds_write_b16_d16_hi v166, v86 offset:48
	ds_write_b16 v166, v87 offset:96
	ds_write_b16_d16_hi v166, v87 offset:144
	ds_write_b16 v166, v88 offset:192
	ds_write_b16_d16_hi v166, v88 offset:240
	ds_write_b16 v166, v89 offset:288
	ds_write_b16_d16_hi v166, v89 offset:336
	s_waitcnt lgkmcnt(0)
	s_waitcnt lgkmcnt(0)
	ds_read_b128 v[74:77], v164
	s_waitcnt lgkmcnt(0)
	s_and_b64 vcc, exec, s[6:7]
	s_mov_b64 s[42:43], -1
	s_cbranch_vccnz .LBB0_246
	v_lshlrev_b32_e32 v142, 1, v126
	v_lshl_add_u64 v[86:87], s[40:41], 0, v[142:143]
	v_lshl_add_u64 v[68:69], v[68:69], 1, v[86:87]
	s_mov_b64 s[42:43], 0
	s_waitcnt lgkmcnt(0)
	global_store_dwordx4 v[68:69], v[74:77], off nt
.LBB0_246:
	s_andn2_b64 vcc, exec, s[42:43]
	s_cbranch_vccnz .LBB0_248
	s_ashr_i32 s13, s12, 31
	s_lshl_b64 s[42:43], s[12:13], 8
	s_add_u32 s13, s42, s79
	s_addc_u32 s43, s43, 0
	s_bfe_u32 s33, s31, 0x40005
	s_or_b32 s42, s13, s33
	s_or_b64 s[42:43], s[42:43], s[10:11]
	s_lshl_b64 s[42:43], s[42:43], 12
	s_add_u32 s42, s40, s42
	s_addc_u32 s43, s41, s43
	v_lshl_add_u64 v[68:69], s[42:43], 0, v[144:145]
	s_waitcnt lgkmcnt(0)
	global_store_dwordx4 v[68:69], v[74:77], off offset:1024 nt
.LBB0_248:
	ds_write_b16 v166, v82
	ds_write_b16_d16_hi v166, v82 offset:48
	ds_write_b16 v166, v83 offset:96
	ds_write_b16_d16_hi v166, v83 offset:144
	ds_write_b16 v166, v84 offset:192
	ds_write_b16_d16_hi v166, v84 offset:240
	ds_write_b16 v166, v85 offset:288
	ds_write_b16_d16_hi v166, v85 offset:336
	s_waitcnt lgkmcnt(0)
	s_waitcnt lgkmcnt(0)
	ds_read_b128 v[74:77], v164
	s_waitcnt lgkmcnt(0)
	v_add_u32_e32 v68, s1, v172
	s_mov_b64 s[42:43], -1
	s_and_b64 vcc, exec, s[6:7]
	v_ashrrev_i32_e32 v69, 31, v68
	s_cbranch_vccnz .LBB0_250
	v_lshlrev_b32_e32 v142, 1, v130
	v_lshl_add_u64 v[82:83], s[40:41], 0, v[142:143]
	v_lshl_add_u64 v[82:83], v[68:69], 1, v[82:83]
	s_mov_b64 s[42:43], 0
	s_waitcnt lgkmcnt(0)
	global_store_dwordx4 v[82:83], v[74:77], off nt
; __device__ __forceinline__ unsigned pk2(float lo, float hi) { const f32x2 v = {lo, hi}; const bf16x2_t b = __builtin_convertvector(v, bf16x2_t); return __builtin_bit_cast(unsigned, b); }
;     __device__ __forceinline__ void operator()(const f32x4 (&acc)[2][2][4][2], const pg8::Unit& u, int wr, int wc, int fr, int fq) const {
;     ...
;                     for (int bj = 0; bj < 2; ++bj) {
; #pragma unroll
;                         for (int n = 0; n < 2; ++n) { const f32x4 v = acc[ai][bj][m][n]; const unsigned w0 = pk2(v[0], v[1]), w1 = pk2(v[2], v[3]);
;                             bf16_t* p = T + (8 * fq + 4 * n) * 24 + fr;
;                             p[0] = (bf16_t)(w0 & 0xffffu); p[24] = (bf16_t)(w0 >> 16); p[48] = (bf16_t)(w1 & 0xffffu); p[72] = (bf16_t)(w1 >> 16); }
;                         asm volatile("s_waitcnt lgkmcnt(0)" ::: "memory");
;                         const u32x4 w = *(const u32x4*)(T + col * 24 + half * 8);
;                         asm volatile("s_waitcnt lgkmcnt(0)" ::: "memory");
;                         const int dvg = colt + bj * 128 + wc * 32 + col;
;                         if (isb) { const size_t gc = (size_t)u.pm * 4 + ai * 2 + wr;
;                             *(u32x4*)(VO + ((((gc * 4 + (dvg >> 9)) * 16 + ((dvg >> 5) & 15)) * 4 + m) * 64 + half * 32 + col) * 8) = w; }
;                         else *(u32x4*)(VO + (size_t)dvg * MR + (size_t)(u.pm * 256 + ai * 128 + wr * 64 + m * 16 + half * 8)) = w;
;                     }
.LBB0_250:
	s_andn2_b64 vcc, exec, s[42:43]
	s_cbranch_vccnz .LBB0_252
	s_ashr_i32 s13, s12, 31
	s_lshl_b64 s[42:43], s[12:13], 8
	s_add_u32 s13, s42, s79
	s_addc_u32 s43, s43, 0
	s_lshr_b32 s33, s3, 5
	s_and_b32 s33, s33, 11
	s_or_b32 s42, s13, s33
	s_or_b64 s[42:43], s[42:43], s[10:11]
	s_lshl_b64 s[42:43], s[42:43], 12
	s_add_u32 s42, s40, s42
	s_addc_u32 s43, s41, s43
	v_lshl_add_u64 v[82:83], s[42:43], 0, v[144:145]
	s_waitcnt lgkmcnt(0)
	global_store_dwordx4 v[82:83], v[74:77], off offset:2048 nt
.LBB0_252:
	ds_write_b16 v166, v78
	ds_write_b16_d16_hi v166, v78 offset:48
	ds_write_b16 v166, v79 offset:96
	ds_write_b16_d16_hi v166, v79 offset:144
	ds_write_b16 v166, v80 offset:192
	ds_write_b16_d16_hi v166, v80 offset:240
	ds_write_b16 v166, v81 offset:288
	ds_write_b16_d16_hi v166, v81 offset:336
	s_waitcnt lgkmcnt(0)
	s_waitcnt lgkmcnt(0)
	ds_read_b128 v[74:77], v164
	s_waitcnt lgkmcnt(0)
	s_and_b64 vcc, exec, s[6:7]
	s_mov_b64 s[42:43], -1
	s_cbranch_vccnz .LBB0_254
	v_lshlrev_b32_e32 v142, 1, v126
	v_lshl_add_u64 v[78:79], s[40:41], 0, v[142:143]
	v_lshl_add_u64 v[68:69], v[68:69], 1, v[78:79]
	s_mov_b64 s[42:43], 0
	s_waitcnt lgkmcnt(0)
	global_store_dwordx4 v[68:69], v[74:77], off nt
.LBB0_254:
	s_andn2_b64 vcc, exec, s[42:43]
	s_cbranch_vccnz .LBB0_256
	s_ashr_i32 s13, s12, 31
	s_lshl_b64 s[42:43], s[12:13], 8
	s_add_u32 s13, s42, s79
	s_addc_u32 s43, s43, 0
	s_bfe_u32 s33, s31, 0x40005
	s_or_b32 s42, s13, s33
	s_or_b64 s[42:43], s[42:43], s[10:11]
	s_lshl_b64 s[42:43], s[42:43], 12
	s_add_u32 s42, s40, s42
	s_addc_u32 s43, s41, s43
	v_lshl_add_u64 v[68:69], s[42:43], 0, v[144:145]
	s_waitcnt lgkmcnt(0)
	global_store_dwordx4 v[68:69], v[74:77], off offset:2048 nt
.LBB0_256:
	ds_write_b16 v166, v70
	ds_write_b16_d16_hi v166, v70 offset:48
	ds_write_b16 v166, v71 offset:96
	ds_write_b16_d16_hi v166, v71 offset:144
	ds_write_b16 v166, v72 offset:192
	ds_write_b16_d16_hi v166, v72 offset:240
	ds_write_b16 v166, v73 offset:288
	ds_write_b16_d16_hi v166, v73 offset:336
	s_waitcnt lgkmcnt(0)
	ds_read_b128 v[68:71], v164
	s_waitcnt lgkmcnt(0)
	v_add_u32_e32 v72, s1, v173
	s_mov_b64 s[42:43], -1
	s_and_b64 vcc, exec, s[6:7]
	v_ashrrev_i32_e32 v73, 31, v72
	s_cbranch_vccnz .LBB0_258
	v_lshlrev_b32_e32 v142, 1, v130
	s_waitcnt lgkmcnt(0)
	v_lshl_add_u64 v[74:75], s[40:41], 0, v[142:143]
	v_lshl_add_u64 v[74:75], v[72:73], 1, v[74:75]
	s_mov_b64 s[42:43], 0
	global_store_dwordx4 v[74:75], v[68:71], off nt
.LBB0_258:
	s_andn2_b64 vcc, exec, s[42:43]
	s_cbranch_vccnz .LBB0_260
	s_ashr_i32 s13, s12, 31
	s_lshl_b64 s[42:43], s[12:13], 8
	s_add_u32 s1, s42, s79
	s_addc_u32 s43, s43, 0
	s_lshr_b32 s3, s3, 5
	s_and_b32 s3, s3, 11
	s_or_b32 s42, s1, s3
	s_or_b64 s[42:43], s[42:43], s[10:11]
	s_lshl_b64 s[42:43], s[42:43], 12
	s_add_u32 s42, s40, s42
	s_addc_u32 s43, s41, s43
	s_waitcnt lgkmcnt(0)
	v_lshl_add_u64 v[74:75], s[42:43], 0, v[144:145]
	global_store_dwordx4 v[74:75], v[68:71], off offset:3072 nt
.LBB0_260:
	ds_write_b16 v166, v64
	ds_write_b16_d16_hi v166, v64 offset:48
	ds_write_b16 v166, v65 offset:96
	ds_write_b16_d16_hi v166, v65 offset:144
	ds_write_b16 v166, v66 offset:192
	ds_write_b16_d16_hi v166, v66 offset:240
	ds_write_b16 v166, v67 offset:288
	ds_write_b16_d16_hi v166, v67 offset:336
	s_waitcnt lgkmcnt(0)
	ds_read_b128 v[64:67], v164
	s_waitcnt lgkmcnt(0)
	s_and_b64 vcc, exec, s[6:7]
	s_mov_b64 s[6:7], -1
	s_cbranch_vccnz .LBB0_262
	v_lshlrev_b32_e32 v142, 1, v126
	s_waitcnt lgkmcnt(0)
	v_lshl_add_u64 v[68:69], s[40:41], 0, v[142:143]
	v_lshl_add_u64 v[68:69], v[72:73], 1, v[68:69]
	s_mov_b64 s[6:7], 0
	global_store_dwordx4 v[68:69], v[64:67], off nt
.LBB0_262:
	s_andn2_b64 vcc, exec, s[6:7]
	s_cbranch_vccnz .LBB0_264
	s_ashr_i32 s13, s12, 31
	s_lshl_b64 s[6:7], s[12:13], 8
	s_add_u32 s1, s6, s79
	s_addc_u32 s7, s7, 0
	s_bfe_u32 s3, s31, 0x40005
	s_or_b32 s6, s1, s3
	s_or_b64 s[6:7], s[6:7], s[10:11]
	s_lshl_b64 s[6:7], s[6:7], 12
	s_add_u32 s6, s40, s6
	s_addc_u32 s7, s41, s7
	s_waitcnt lgkmcnt(0)
	v_lshl_add_u64 v[68:69], s[6:7], 0, v[144:145]
	global_store_dwordx4 v[68:69], v[64:67], off offset:3072 nt

;     __device__ __forceinline__ void operator()(const f32x4 (&acc)[2][2][4][2], const pg8::Unit& u, int wr, int wc, int fr, int fq) const {
;     ...
;         if (pn == 56) {
;             if (wc == 0) { float* BG = (float*)(ws + WS_BG);
; #pragma unroll
;                 for (int ai = 0; ai < 2; ++ai)
; #pragma unroll
;                     for (int m = 0; m < 4; ++m) { float* p = BG + (size_t)(row0 + ai * 128 + m * 16) * 32 + 8 * fq;
;                         *(f32x4*)p = acc[ai][0][m][0]; *(f32x4*)(p + 4) = acc[ai][0][m][1]; } }
;             return;
.LBB0_270:
	v_ashrrev_i32_e32 v157, 31, v156
	s_waitcnt lgkmcnt(0)
	v_lshlrev_b64 v[64:65], 7, v[156:157]
	v_lshl_add_u64 v[64:65], v[146:147], 0, v[64:65]
	global_store_dwordx4 v[64:65], v[60:63], off nt
	global_store_dwordx4 v[64:65], v[56:59], off offset:16 nt
	s_nop 1
	v_or_b32_e32 v56, 16, v156
	v_ashrrev_i32_e32 v57, 31, v56
	v_lshlrev_b64 v[56:57], 7, v[56:57]
	v_lshl_add_u64 v[56:57], v[146:147], 0, v[56:57]
	global_store_dwordx4 v[56:57], v[52:55], off nt
	global_store_dwordx4 v[56:57], v[48:51], off offset:16 nt
	s_nop 1
	v_or_b32_e32 v48, 32, v156
	v_ashrrev_i32_e32 v49, 31, v48
	v_lshlrev_b64 v[48:49], 7, v[48:49]
	v_lshl_add_u64 v[48:49], v[146:147], 0, v[48:49]
	global_store_dwordx4 v[48:49], v[44:47], off nt
	global_store_dwordx4 v[48:49], v[40:43], off offset:16 nt
	s_nop 1
	v_or_b32_e32 v40, 48, v156
	v_ashrrev_i32_e32 v41, 31, v40
	v_lshlrev_b64 v[40:41], 7, v[40:41]
	v_lshl_add_u64 v[40:41], v[146:147], 0, v[40:41]
	global_store_dwordx4 v[40:41], v[36:39], off nt
	global_store_dwordx4 v[40:41], v[32:35], off offset:16 nt
	s_nop 1
	v_add_co_u32_e32 v34, vcc, s54, v64
	v_lshl_add_u64 v[32:33], v[64:65], 0, s[22:23]
	s_nop 0
	v_addc_co_u32_e32 v35, vcc, 0, v65, vcc
	global_store_dwordx4 v[34:35], v[28:31], off nt
	global_store_dwordx4 v[32:33], v[24:27], off offset:16 nt
	s_nop 1
	v_lshl_add_u64 v[24:25], v[64:65], 0, s[24:25]
	global_store_dwordx4 v[34:35], v[20:23], off offset:2048 nt
	global_store_dwordx4 v[24:25], v[16:19], off offset:16 nt
	s_nop 1
	v_add_co_u32_e32 v18, vcc, 0x5000, v64
	v_lshl_add_u64 v[16:17], v[64:65], 0, s[26:27]
	s_nop 0
	v_addc_co_u32_e32 v19, vcc, 0, v65, vcc
	global_store_dwordx4 v[18:19], v[12:15], off nt
	global_store_dwordx4 v[16:17], v[8:11], off offset:16 nt
	s_nop 1
	v_lshl_add_u64 v[8:9], v[64:65], 0, s[28:29]
	global_store_dwordx4 v[18:19], v[4:7], off offset:2048 nt
	global_store_dwordx4 v[8:9], v[0:3], off offset:16 nt
	s_andn2_b64 vcc, exec, s[4:5]
	s_mov_b64 s[4:5], -1
	s_cbranch_vccnz .LBB0_180
	s_branch .LBB0_268

; __device__ __forceinline__ void phase_scan(const Args& a, unsigned char* smem, int tid, int lane, int wave) {
;     ...
;     for (int wu = blockIdx.x; wu < 256; wu += gridDim.x) {
;         const int combo = (wu & 7) * 2 + (wu >> 7), sl = (wu >> 3) & 15;
;         const int b = combo >> 3, h = (combo >> 1) & 3, dir = combo & 1;
;         const bf16_t* QE = (const bf16_t*)(a.ws + (dir ? WS_AZ : WS_BQ));
;         const bf16_t* KDT = (const bf16_t*)(a.ws + (dir ? WS_AVT : WS_AK));
;         const bf16_t* ATT = (const bf16_t*)(a.ws + WS_ATT) + (size_t)dir * 512 * 4 * 4096;
;         const float* DL = (const float*)(a.ws + WS_DL) + (size_t)dir * 520 * 1024;
;         const bf16_t* BVF = (const bf16_t*)(a.ws + WS_BVT) + (size_t)lane * 8;
;         bf16_t* O = (bf16_t*)((unsigned char*)a.out + (dir ? DO_OB : DO_OF));
;         f32x16 S;
; #pragma unroll
;         for (int i = 0; i < 16; ++i) S[i] = 0.f;
;         bf16x8 vB[4], qeA[4], atA; f32x4 dl[4];
;         bf16x8 nqe[4], nat;
;         u32x4 gcur = {0u, 0u, 0u, 0u}, gnxt = {0u, 0u, 0u, 0u};
;     ...
;         const unsigned char* scb; unsigned scsg;
;         { const int q16s = sl * 16 + (lane & 15);
;           if (wave == 5) { if (lane < 16) { scb = (const unsigned char*)KDT + (size_t)h * 32768 + (size_t)q16s * 128; scsg = 131072u; }
;                            else if (lane < 32) { scb = (const unsigned char*)QE + (size_t)h * 512 + (size_t)(q16s >> 2) * 2048 + (q16s & 3) * 128; scsg = 131072u; }
;                            else if (lane < 36) { scb = (const unsigned char*)ATT + (size_t)h * 8192 + (size_t)(sl * 4 + lane - 32) * 128; scsg = 32768u; }
;                            else { scb = (const unsigned char*)DL + (size_t)h * 1024 + (lane & 7) * 128; scsg = 4096u; } }
;           else if (wave == 6) { scb = (const unsigned char*)(a.ws + WS_BVT) + (size_t)(h * 16 + sl) * 4096 + (size_t)(lane & 31) * 128; scsg = 262144u; }
;           else { scb = (const unsigned char*)DL + (size_t)h * 1024; scsg = 0u; } }
.LBB0_596:
	s_cmp_lt_i32 s96, 6
	s_cselect_b64 s[6:7], -1, 0
	s_and_b64 s[12:13], s[6:7], s[4:5]
	s_andn2_b64 vcc, exec, s[12:13]
	s_cbranch_vccnz .LBB0_704
	s_cmpk_gt_i32 s2, 0xff
	s_cbranch_scc1 .LBB0_703
	s_mov_b64 exec, -1
	s_mov_b32 s14, s2
.Lscan_unit:
	s_and_b32 s40, s14, 7
	s_lshl_b32 s40, s40, 1
	s_lshr_b32 s41, s14, 7
	s_add_i32 s40, s40, s41
	s_lshr_b32 s18, s14, 3
	s_and_b32 s18, s18, 15
	s_lshr_b32 s15, s40, 3
	s_bfe_u32 s16, s40, 0x20001
	s_and_b32 s17, s40, 1
	s_cmp_eq_u32 s17, 1
	s_mov_b32 s41, 0x4200000
	s_cselect_b32 s41, 0x8300000, s41
	s_lshl_b32 s42, s16, 15
	s_add_u32 s41, s41, s42
	s_add_u32 s20, s94, s41
	s_addc_u32 s21, s95, 0
	s_cmp_eq_u32 s17, 1
	s_mov_b32 s41, 0x10501000
	s_cselect_b32 s41, 0xc401000, s41
	s_lshl_b32 s42, s16, 9
	s_add_u32 s41, s41, s42
	s_add_u32 s22, s94, s41
	s_addc_u32 s23, s95, 0
	s_lshl_b32 s41, s17, 24
	s_add_u32 s41, s41, 0x3a710000
	s_lshl_b32 s42, s16, 13
	s_add_u32 s41, s41, s42
	s_add_u32 s24, s94, s41
	s_addc_u32 s25, s95, 0
	s_mul_i32 s41, s17, 0x208000
	s_add_u32 s41, s41, 0x3c710000
	s_lshl_b32 s42, s16, 10
	s_add_u32 s41, s41, s42
	s_add_u32 s46, s94, s41
	s_addc_u32 s47, s95, 0
	s_lshl_b32 s41, s16, 4
	s_add_i32 s41, s41, s18
	s_lshl_b32 s41, s41, 12
	s_add_u32 s41, s41, 0x18700000
	s_add_u32 s48, s94, s41
	s_addc_u32 s49, s95, 0
	s_lshl_b32 s41, s17, 27
	s_add_u32 s26, s92, s41
	s_addc_u32 s27, s93, 0
	s_lshl_b32 s28, s15, 8
	s_cmp_eq_u32 s17, 1
	s_cselect_b32 s29, -1, 1
	s_cselect_b32 s41, 255, 0
	s_add_i32 s28, s28, s41
	s_cmp_lt_u32 s0, 5
	s_cselect_b32 s31, 4, 6
	v_lshrrev_b32_e32 v251, 5, v160
	v_and_b32_e32 v194, 31, v160
	v_lshlrev_b32_e32 v232, 11, v251
	v_lshl_add_u32 v232, v194, 4, v232
	s_lshl_b32 s41, s0, 14
	v_add_u32_e32 v232, s41, v232
	s_cmp_lt_u32 s0, 4
	s_cselect_b32 s41, 0, 8192
	s_cselect_b32 s42, 8192, 0
	v_add_u32_e32 v233, s42, v232
	v_add_u32_e32 v232, s41, v232
	v_lshlrev_b32_e32 v234, 4, v160
	s_lshl_b32 s41, s0, 12
	v_add_u32_e32 v235, s41, v234
	v_add_u32_e32 v246, 0x10000, v234
	s_and_b32 s42, s0, 3
	s_lshl_b32 s42, s42, 10
	v_add_u32_e32 v248, s42, v246
	s_lshl_b32 s41, s0, 10
	v_lshlrev_b32_e32 v247, 4, v251
	s_lshl_b32 s42, s0, 7
	s_add_i32 s42, s42, 0x12000
	v_add_u32_e32 v247, s42, v247
	s_cmp_lt_u32 s0, 4
	s_cbranch_scc0 .Lscan_stw_ge4
	v_add_u32_e32 v239, s41, v246
	v_add_u32_e32 v240, 4096, v239
	s_branch .Lscan_stw_done
.Lscan_stw_ge4:
	s_cmp_eq_u32 s0, 4
	s_cbranch_scc0 .Lscan_stw_gt4
	v_add_u32_e32 v239, 0x12000, v234
	v_add_u32_e32 v240, 1024, v239
	s_branch .Lscan_stw_done
.Lscan_stw_gt4:
	s_lshl_b32 s42, s0, 11
	s_add_i32 s42, s42, 0x10000
	v_add_u32_e32 v239, s42, v234
	v_add_u32_e32 v240, 1024, v239
.Lscan_stw_done:
	v_lshlrev_b32_e32 v241, 2, v160
	v_xor_b32_e32 v242, 32, v160
	v_lshlrev_b32_e32 v242, 2, v242
	s_lshl_b32 s41, s0, 12
	s_cmp_lt_u32 s0, 4
	s_cselect_b32 s42, 0, 2048
	s_cselect_b32 s43, 2048, 0
	s_add_i32 s42, s42, s41
	s_add_i32 s43, s43, s41
	v_add_u32_e32 v243, s43, v241
	v_add_u32_e32 v244, s43, v242
	v_add_u32_e32 v241, s42, v241
	v_add_u32_e32 v242, s42, v242
	v_lshrrev_b32_e32 v251, 4, v161
	v_lshlrev_b32_e32 v251, 1, v251
	v_and_b32_e32 v194, 15, v161
	v_lshlrev_b32_e32 v194, 1, v194
	v_lshlrev_b32_e32 v249, 12, v251
	v_lshl_add_u32 v249, v194, 1, v249
	s_lshl_b32 s41, s16, 10
	s_lshl_b32 s42, s18, 6
	s_add_i32 s41, s41, s42
	v_add_u32_e32 v249, s41, v249
	v_add_u32_e32 v250, 4096, v249
	v_lshrrev_b32_e32 v245, 5, v251
	v_and_b32_e32 v251, 31, v251
	v_lshrrev_b32_e32 v228, 3, v251
	v_bfe_u32 v229, v251, 1, 1
	v_lshl_add_u32 v228, v228, 1, v229
	v_lshl_add_u32 v245, v245, 3, v228
	v_bfe_u32 v230, v251, 2, 1
	v_lshl_add_u32 v230, v230, 5, v194
	v_and_b32_e32 v228, 1, v228
	v_lshlrev_b32_e32 v228, 5, v228
	v_xor_b32_e32 v230, v230, v228
	v_lshl_add_u32 v245, v245, 6, v230
	v_lshlrev_b32_e32 v245, 2, v245
	s_cmp_lt_u32 s0, 4
	s_cbranch_scc0 .Lscan_gb_ge4
	s_lshl_b32 s41, s0, 10
	v_add_u32_e32 v194, s41, v234
	v_mov_b32_e32 v195, 0
	v_lshl_add_u64 v[236:237], s[48:49], 0, v[194:195]
	v_mov_b32_e32 v238, 0x40000
	s_branch .Lscan_gb_done
.Lscan_gb_ge4:
	s_cmp_eq_u32 s0, 4
	s_cbranch_scc0 .Lscan_gb_ge5
	v_mov_b32_e32 v194, v234
	v_mov_b32_e32 v195, 0
	v_lshl_add_u64 v[236:237], s[46:47], 0, v[194:195]
	v_mov_b32_e32 v238, 0x1000
	s_branch .Lscan_gb_done
.Lscan_gb_ge5:
	s_cmp_eq_u32 s0, 5
	s_cbranch_scc0 .Lscan_gb_ge6
	v_and_b32_e32 v251, 15, v160
	s_lshl_b32 s41, s18, 4
	v_add_u32_e32 v251, s41, v251
	v_and_b32_e32 v194, 7, v160
	v_lshlrev_b32_e32 v194, 7, v194
	v_mov_b32_e32 v195, 0
	v_lshl_add_u64 v[236:237], s[46:47], 0, v[194:195]
	v_mov_b32_e32 v238, 0x1000
	v_subrev_u32_e32 v194, 32, v160
	s_lshl_b32 s41, s18, 2
	v_add_u32_e32 v194, s41, v194
	v_lshlrev_b32_e32 v194, 7, v194
	v_mov_b32_e32 v195, 0
	v_lshl_add_u64 v[228:229], s[24:25], 0, v[194:195]
	v_cmp_gt_u32_e32 vcc, 36, v160
	s_nop 1
	v_cndmask_b32_e32 v236, v236, v228, vcc
	v_cndmask_b32_e32 v237, v237, v229, vcc
	v_mov_b32_e32 v230, 0x8000
	v_cndmask_b32_e32 v238, v238, v230, vcc
	v_lshrrev_b32_e32 v194, 2, v251
	v_lshlrev_b32_e32 v194, 11, v194
	v_and_b32_e32 v230, 3, v251
	v_lshl_add_u32 v194, v230, 7, v194
	v_mov_b32_e32 v195, 0
	s_sub_u32 s50, s22, 4096
	s_subb_u32 s51, s23, 0
	v_lshl_add_u64 v[228:229], s[50:51], 0, v[194:195]
	v_cmp_gt_u32_e32 vcc, 32, v160
	s_nop 1
	v_cndmask_b32_e32 v236, v236, v228, vcc
	v_cndmask_b32_e32 v237, v237, v229, vcc
	v_mov_b32_e32 v230, 0x20000
	v_cndmask_b32_e32 v238, v238, v230, vcc
	v_lshlrev_b32_e32 v194, 7, v251
	v_mov_b32_e32 v195, 0
	v_lshl_add_u64 v[228:229], s[20:21], 0, v[194:195]
	v_cmp_gt_u32_e32 vcc, 16, v160
	s_nop 1
	v_cndmask_b32_e32 v236, v236, v228, vcc
	v_cndmask_b32_e32 v237, v237, v229, vcc
	s_branch .Lscan_gb_done
; __device__ __forceinline__ f32x16 mfma32(bf16x8 a, bf16x8 b, f32x16 c) { return __builtin_amdgcn_mfma_f32_32x32x16_bf16(a, b, c, 0, 0, 0); }
; #define SCAN_GLOAD(step, G_) do { const int gc_ = SCAN_GC(step); \
;         if (wave < 4) G_ = *(const u32x4*)(BVF + ((((size_t)gc_ * 4 + h) * 16 + sl) * 4 + wave) * 512); \
;         else if (wave == 4) G_ = *(const u32x4*)(DL + ((size_t)gc_ * 4 + h) * 256 + lane * 4); } while (0)
; #define SCAN_GSTORE(buf, G_) do { if (wave < 4) *(u32x4*)(vst + (((buf) * 4 + wave) * 64 + lane) * 16) = G_; \
;         else if (wave == 4) *(u32x4*)(dst + (buf) * 1024 + lane * 16) = G_; } while (0)
; #define SCAN_LREAD(buf, VB_, DL_) do { _Pragma("unroll") for (int q_ = 0; q_ < 4; ++q_) { \
;         VB_[q_] = *(const bf16x8*)(vst + (((buf) * 4 + q_) * 64 + lane) * 16); \
;         DL_[q_] = *(const f32x4*)(dst + (buf) * 1024 + (kb * 32 + 8 * q_ + 4 * hh) * 4); } } while (0)
; __device__ __forceinline__ void phase_scan(const Args& a, unsigned char* smem, int tid, int lane, int wave) {
;     ...
;         __syncthreads();
;         SCAN_GLOAD(0, gcur); SCAN_GSTORE(0, gcur);
;         SCAN_GLOAD(1, gcur);
;         SCAN_LOAD(0, qeA, atA);
;         __syncthreads();
;         SCAN_LREAD(0, vB, dl);
;         __builtin_amdgcn_s_waitcnt(0x0F70);
;     ...
;             for (int i = 0; i < 16; ++i) S[i] *= dl[i >> 2][i & 3];
; #pragma unroll
;             for (int ks = 0; ks < 4; ++ks) S = mfma32(kdA[ks], vB[ks], S);
.Lscan_gb_ge6:
	s_cmp_eq_u32 s0, 6
	s_cbranch_scc0 .Lscan_gb_7
	v_and_b32_e32 v194, 31, v160
	v_lshlrev_b32_e32 v194, 7, v194
	v_mov_b32_e32 v195, 0
	v_lshl_add_u64 v[236:237], s[48:49], 0, v[194:195]
	v_mov_b32_e32 v238, 0x40000
	s_branch .Lscan_gb_done
.Lscan_gb_7:
	v_mov_b32_e32 v194, 0
	v_mov_b32_e32 v195, 0
	v_lshl_add_u64 v[236:237], s[46:47], 0, v[194:195]
	v_mov_b32_e32 v238, 0
.Lscan_gb_done:
	v_lshrrev_b32_e32 v251, 5, v160
	v_lshlrev_b32_e32 v251, 4, v251
	s_lshl_b32 s41, s0, 7
	v_add_u32_e32 v251, s41, v251
	s_cmp_eq_u32 s17, 1
	s_cselect_b32 s40, 3, 0
	s_lshl_b32 s41, s15, 2
	s_add_i32 s40, s40, s41
	s_addk_i32 s40, 0x200
	s_lshl_b32 s41, s40, 17
	s_add_u32 s32, s20, s41
	s_addc_u32 s33, s21, 0
	s_lshl_b32 s41, s40, 18
	s_add_u32 s34, s48, s41
	s_addc_u32 s35, s49, 0
	s_lshl_b32 s41, s40, 12
	s_add_u32 s36, s46, s41
	s_addc_u32 s37, s47, 0
	global_load_dwordx4 v[16:19], v235, s[32:33]
	global_load_dwordx4 v[20:23], v235, s[32:33] offset:1024
	global_load_dwordx4 v[24:27], v235, s[32:33] offset:2048
	global_load_dwordx4 v[28:31], v235, s[32:33] offset:3072
	global_load_dwordx4 v[80:83], v234, s[34:35]
	global_load_dwordx4 v[84:87], v234, s[34:35] offset:1024
	global_load_dwordx4 v[88:91], v234, s[34:35] offset:2048
	global_load_dwordx4 v[92:95], v234, s[34:35] offset:3072
	global_load_dwordx4 v[144:147], v251, s[36:37]
	global_load_dwordx4 v[148:151], v251, s[36:37] offset:32
	global_load_dwordx4 v[152:155], v251, s[36:37] offset:64
	global_load_dwordx4 v[156:159], v251, s[36:37] offset:96
	s_cmp_eq_u32 s17, 1
	s_cselect_b32 s40, 2, 1
	s_lshl_b32 s41, s15, 2
	s_add_i32 s40, s40, s41
	s_addk_i32 s40, 0x200
	s_lshl_b32 s41, s40, 17
	s_add_u32 s32, s20, s41
	s_addc_u32 s33, s21, 0
	s_lshl_b32 s41, s40, 18
	s_add_u32 s34, s48, s41
	s_addc_u32 s35, s49, 0
	s_lshl_b32 s41, s40, 12
	s_add_u32 s36, s46, s41
	s_addc_u32 s37, s47, 0
	global_load_dwordx4 v[32:35], v235, s[32:33]
	global_load_dwordx4 v[36:39], v235, s[32:33] offset:1024
	global_load_dwordx4 v[40:43], v235, s[32:33] offset:2048
	global_load_dwordx4 v[44:47], v235, s[32:33] offset:3072
	global_load_dwordx4 v[96:99], v234, s[34:35]
	global_load_dwordx4 v[100:103], v234, s[34:35] offset:1024
	global_load_dwordx4 v[104:107], v234, s[34:35] offset:2048
	global_load_dwordx4 v[108:111], v234, s[34:35] offset:3072
	global_load_dwordx4 v[162:165], v251, s[36:37]
	global_load_dwordx4 v[166:169], v251, s[36:37] offset:32
	global_load_dwordx4 v[170:173], v251, s[36:37] offset:64
	global_load_dwordx4 v[174:177], v251, s[36:37] offset:96
	s_cmp_eq_u32 s17, 1
	s_cselect_b32 s40, 1, 2
	s_lshl_b32 s41, s15, 2
	s_add_i32 s40, s40, s41
	s_addk_i32 s40, 0x200
	s_lshl_b32 s41, s40, 17
	s_add_u32 s32, s20, s41
	s_addc_u32 s33, s21, 0
	s_lshl_b32 s41, s40, 18
	s_add_u32 s34, s48, s41
	s_addc_u32 s35, s49, 0
	s_lshl_b32 s41, s40, 12
	s_add_u32 s36, s46, s41
	s_addc_u32 s37, s47, 0
	global_load_dwordx4 v[48:51], v235, s[32:33]
	global_load_dwordx4 v[52:55], v235, s[32:33] offset:1024
	global_load_dwordx4 v[56:59], v235, s[32:33] offset:2048
	global_load_dwordx4 v[60:63], v235, s[32:33] offset:3072
	global_load_dwordx4 v[112:115], v234, s[34:35]
	global_load_dwordx4 v[116:119], v234, s[34:35] offset:1024
	global_load_dwordx4 v[120:123], v234, s[34:35] offset:2048
	global_load_dwordx4 v[124:127], v234, s[34:35] offset:3072
	global_load_dwordx4 v[178:181], v251, s[36:37]
	global_load_dwordx4 v[182:185], v251, s[36:37] offset:32
	global_load_dwordx4 v[186:189], v251, s[36:37] offset:64
	global_load_dwordx4 v[190:193], v251, s[36:37] offset:96
	s_cmp_eq_u32 s17, 1
	s_cselect_b32 s40, 0, 3
	s_lshl_b32 s41, s15, 2
	s_add_i32 s40, s40, s41
	s_addk_i32 s40, 0x200
	s_lshl_b32 s41, s40, 17
	s_add_u32 s32, s20, s41
	s_addc_u32 s33, s21, 0
	s_lshl_b32 s41, s40, 18
	s_add_u32 s34, s48, s41
	s_addc_u32 s35, s49, 0
	s_lshl_b32 s41, s40, 12
	s_add_u32 s36, s46, s41
	s_addc_u32 s37, s47, 0
	global_load_dwordx4 v[64:67], v235, s[32:33]
	global_load_dwordx4 v[68:71], v235, s[32:33] offset:1024
	global_load_dwordx4 v[72:75], v235, s[32:33] offset:2048
	global_load_dwordx4 v[76:79], v235, s[32:33] offset:3072
	global_load_dwordx4 v[128:131], v234, s[34:35]
	global_load_dwordx4 v[132:135], v234, s[34:35] offset:1024
	global_load_dwordx4 v[136:139], v234, s[34:35] offset:2048
	global_load_dwordx4 v[140:143], v234, s[34:35] offset:3072
	global_load_dwordx4 v[194:197], v251, s[36:37]
	global_load_dwordx4 v[198:201], v251, s[36:37] offset:32
	global_load_dwordx4 v[202:205], v251, s[36:37] offset:64
	global_load_dwordx4 v[206:209], v251, s[36:37] offset:96
	s_lshl_b32 s41, s0, 10
	v_add_u32_e32 v251, s41, v234
	s_waitcnt vmcnt(36)
	v_mfma_f32_32x32x16_bf16 v[0:15], v[16:19], v[80:83], 0
	v_mfma_f32_32x32x16_bf16 v[0:15], v[20:23], v[84:87], v[0:15]
	v_mfma_f32_32x32x16_bf16 v[0:15], v[24:27], v[88:91], v[0:15]
	v_mfma_f32_32x32x16_bf16 v[0:15], v[28:31], v[92:95], v[0:15]
	s_waitcnt vmcnt(24)
	s_nop 15
	v_pk_mul_f32 v[0:1], v[162:163], v[0:1]
	v_pk_mul_f32 v[2:3], v[164:165], v[2:3]
	v_pk_mul_f32 v[4:5], v[166:167], v[4:5]
	v_pk_mul_f32 v[6:7], v[168:169], v[6:7]
	v_pk_mul_f32 v[8:9], v[170:171], v[8:9]
	v_pk_mul_f32 v[10:11], v[172:173], v[10:11]
	v_pk_mul_f32 v[12:13], v[174:175], v[12:13]
	v_pk_mul_f32 v[14:15], v[176:177], v[14:15]
	s_nop 1
	v_mfma_f32_32x32x16_bf16 v[0:15], v[32:35], v[96:99], v[0:15]
	v_mfma_f32_32x32x16_bf16 v[0:15], v[36:39], v[100:103], v[0:15]
	v_mfma_f32_32x32x16_bf16 v[0:15], v[40:43], v[104:107], v[0:15]
	v_mfma_f32_32x32x16_bf16 v[0:15], v[44:47], v[108:111], v[0:15]
	s_waitcnt vmcnt(12)
; __device__ __forceinline__ f32x16 mfma32(bf16x8 a, bf16x8 b, f32x16 c) { return __builtin_amdgcn_mfma_f32_32x32x16_bf16(a, b, c, 0, 0, 0); }
; #define SCAN_GLOAD(step, G_) do { const int gc_ = SCAN_GC(step); \
;         if (wave < 4) G_ = *(const u32x4*)(BVF + ((((size_t)gc_ * 4 + h) * 16 + sl) * 4 + wave) * 512); \
;         else if (wave == 4) G_ = *(const u32x4*)(DL + ((size_t)gc_ * 4 + h) * 256 + lane * 4); } while (0)
; #define SCAN_GSTORE(buf, G_) do { if (wave < 4) *(u32x4*)(vst + (((buf) * 4 + wave) * 64 + lane) * 16) = G_; \
;         else if (wave == 4) *(u32x4*)(dst + (buf) * 1024 + lane * 16) = G_; } while (0)
; #define SCAN_LREAD(buf, VB_, DL_) do { _Pragma("unroll") for (int q_ = 0; q_ < 4; ++q_) { \
;         VB_[q_] = *(const bf16x8*)(vst + (((buf) * 4 + q_) * 64 + lane) * 16); \
;         DL_[q_] = *(const f32x4*)(dst + (buf) * 1024 + (kb * 32 + 8 * q_ + 4 * hh) * 4); } } while (0)
; __device__ __forceinline__ void phase_scan(const Args& a, unsigned char* smem, int tid, int lane, int wave) {
;     ...
;         SCAN_GLOAD(0, gcur); SCAN_GSTORE(0, gcur);
;         SCAN_GLOAD(1, gcur);
;         SCAN_LOAD(0, qeA, atA);
;         __syncthreads();
;         SCAN_LREAD(0, vB, dl);
;         __builtin_amdgcn_s_waitcnt(0x0F70);
;         auto stepf = [&](const int step, unsigned& sc_issue, unsigned& sc_consume) __attribute__((always_inline)) {
;             const int nstep = step < 259 ? step + 1 : step, n2 = step < 258 ? step + 2 : 259;
;             SCAN_LOAD(nstep, nqe, nat);
;             SCAN_GLOAD(n2, gnxt);
;     ...
;             SCAN_LREAD(nbuf, nvB, ndl);
; #pragma unroll
;             for (int i = 0; i < 16; ++i) S[i] *= dl[i >> 2][i & 3];
; #pragma unroll
;             for (int ks = 0; ks < 4; ++ks) S = mfma32(kdA[ks], vB[ks], S);
; #pragma unroll
;             for (int i = 0; i < 4; ++i) { vB[i] = nvB[i]; dl[i] = ndl[i]; qeA[i] = nqe[i]; }
	s_nop 15
	v_pk_mul_f32 v[0:1], v[178:179], v[0:1]
	v_pk_mul_f32 v[2:3], v[180:181], v[2:3]
	v_pk_mul_f32 v[4:5], v[182:183], v[4:5]
	v_pk_mul_f32 v[6:7], v[184:185], v[6:7]
	v_pk_mul_f32 v[8:9], v[186:187], v[8:9]
	v_pk_mul_f32 v[10:11], v[188:189], v[10:11]
	v_pk_mul_f32 v[12:13], v[190:191], v[12:13]
	v_pk_mul_f32 v[14:15], v[192:193], v[14:15]
	s_nop 1
	v_mfma_f32_32x32x16_bf16 v[0:15], v[48:51], v[112:115], v[0:15]
	v_mfma_f32_32x32x16_bf16 v[0:15], v[52:55], v[116:119], v[0:15]
	v_mfma_f32_32x32x16_bf16 v[0:15], v[56:59], v[120:123], v[0:15]
	v_mfma_f32_32x32x16_bf16 v[0:15], v[60:63], v[124:127], v[0:15]
	s_waitcnt vmcnt(0)
	s_nop 15
	v_pk_mul_f32 v[0:1], v[194:195], v[0:1]
	v_pk_mul_f32 v[2:3], v[196:197], v[2:3]
	v_pk_mul_f32 v[4:5], v[198:199], v[4:5]
	v_pk_mul_f32 v[6:7], v[200:201], v[6:7]
	v_pk_mul_f32 v[8:9], v[202:203], v[8:9]
	v_pk_mul_f32 v[10:11], v[204:205], v[10:11]
	v_pk_mul_f32 v[12:13], v[206:207], v[12:13]
	v_pk_mul_f32 v[14:15], v[208:209], v[14:15]
	s_nop 1
	v_mfma_f32_32x32x16_bf16 v[0:15], v[64:67], v[128:131], v[0:15]
	v_mfma_f32_32x32x16_bf16 v[0:15], v[68:71], v[132:135], v[0:15]
	v_mfma_f32_32x32x16_bf16 v[0:15], v[72:75], v[136:139], v[0:15]
	v_mfma_f32_32x32x16_bf16 v[0:15], v[76:79], v[140:143], v[0:15]
	s_nop 15
	s_nop 3
	s_mov_b32 s30, 0
	s_mov_b32 s42, 0
	s_min_u32 s42, s42, 0xff
	s_mul_i32 s42, s42, s29
	s_add_i32 s42, s42, s28
	v_mad_u64_u32 v[194:195], s[44:45], v238, s42, v[236:237]
	global_load_dwordx4 v[204:207], v[194:195], off
	s_mov_b32 s42, 1
	s_min_u32 s42, s42, 0xff
	s_mul_i32 s42, s42, s29
	s_add_i32 s42, s42, s28
	v_mad_u64_u32 v[194:195], s[44:45], v238, s42, v[236:237]
	global_load_dwordx4 v[208:211], v[194:195], off
	s_waitcnt vmcnt(0)
	s_barrier
	ds_write_b128 v239, v[204:207]
	ds_write_b128 v240, v[208:211]
	s_waitcnt lgkmcnt(0)
	s_barrier
	ds_read_b128 v[128:131], v246 offset:0
	ds_read_b128 v[132:135], v246 offset:1024
	ds_read_b128 v[136:139], v246 offset:2048
	ds_read_b128 v[140:143], v246 offset:3072
	ds_read_b128 v[196:199], v248 offset:0
	ds_read_b128 v[162:165], v247 offset:0
	ds_read_b128 v[166:169], v247 offset:32
	ds_read_b128 v[170:173], v247 offset:64
	ds_read_b128 v[174:177], v247 offset:96
	s_mov_b32 s43, s31
	s_mov_b32 s31, 4
	s_mov_b32 s30, -2
	s_add_i32 s40, s30, 2
	s_min_u32 s40, s40, 0xff
	s_mul_i32 s40, s40, s29
	s_add_i32 s40, s40, s28
	s_lshl_b32 s41, s40, 17
	s_add_u32 s32, s20, s41
	s_addc_u32 s33, s21, 0
	s_add_u32 s34, s22, s41
	s_addc_u32 s35, s23, 0
	s_lshl_b32 s41, s40, 15
	s_add_u32 s36, s24, s41
	s_addc_u32 s37, s25, 0
	s_add_i32 s42, s30, s31
	s_min_u32 s42, s42, 0xff
	s_mul_i32 s42, s42, s29
	s_add_i32 s42, s42, s28
	v_mad_u64_u32 v[194:195], s[44:45], v238, s42, v[236:237]
	global_load_dwordx4 v[204:207], v[194:195], off
	global_load_dwordx4 v[76:79], v235, s[32:33]
	global_load_dwordx4 v[80:83], v235, s[32:33] offset:1024
	global_load_dwordx4 v[84:87], v235, s[32:33] offset:2048
	global_load_dwordx4 v[88:91], v235, s[32:33] offset:3072
	global_load_dwordx4 v[56:59], v232, s[34:35] offset:-4096
	global_load_dwordx4 v[60:63], v232, s[34:35]
	global_load_dwordx4 v[64:67], v233, s[34:35] offset:-4096
	global_load_dwordx4 v[68:71], v233, s[34:35]
	global_load_dwordx4 v[72:75], v251, s[36:37]
	s_mov_b32 s30, -1
	s_add_i32 s40, s30, 2
	s_min_u32 s40, s40, 0xff
	s_mul_i32 s40, s40, s29
	s_add_i32 s40, s40, s28
	s_lshl_b32 s41, s40, 17
	s_add_u32 s32, s20, s41
	s_addc_u32 s33, s21, 0
	s_add_u32 s34, s22, s41
	s_addc_u32 s35, s23, 0
	s_lshl_b32 s41, s40, 15
	s_add_u32 s36, s24, s41
	s_addc_u32 s37, s25, 0
	s_add_i32 s42, s30, s31
	s_min_u32 s42, s42, 0xff
	s_mul_i32 s42, s42, s29
	s_add_i32 s42, s42, s28
	v_mad_u64_u32 v[194:195], s[44:45], v238, s42, v[236:237]
	global_load_dwordx4 v[208:211], v[194:195], off
	global_load_dwordx4 v[112:115], v235, s[32:33]
	global_load_dwordx4 v[116:119], v235, s[32:33] offset:1024
	global_load_dwordx4 v[120:123], v235, s[32:33] offset:2048
	global_load_dwordx4 v[124:127], v235, s[32:33] offset:3072
	global_load_dwordx4 v[92:95], v232, s[34:35] offset:-4096
	global_load_dwordx4 v[96:99], v232, s[34:35]
	global_load_dwordx4 v[100:103], v233, s[34:35] offset:-4096
	global_load_dwordx4 v[104:107], v233, s[34:35]
	global_load_dwordx4 v[108:111], v251, s[36:37]
	s_mov_b32 s31, s43
	s_mov_b32 s30, 0
	s_waitcnt lgkmcnt(0)
	s_barrier
; __device__ __forceinline__ void phase_scan(const Args& a, unsigned char* smem, int tid, int lane, int wave) {
;     ...
;         auto stepf = [&](const int step, unsigned& sc_issue, unsigned& sc_consume) __attribute__((always_inline)) {
;             const int nstep = step < 259 ? step + 1 : step, n2 = step < 258 ? step + 2 : 259;
;             SCAN_LOAD(nstep, nqe, nat);
;             SCAN_GLOAD(n2, gnxt);
;     ...
;             { int ss = step + SCOUT; ss = ss > 259 ? 259 : ss; const int gcs = SCAN_GC(ss); sc_issue = *(const unsigned*)(scb + (size_t)gcs * scsg); }
;     ...
;             const int gc = SCAN_GC(step); const size_t row0 = (size_t)gc * 64;
;             bf16x8 kdA[4];
;             { const bf16_t* kp = KDT + (((size_t)gc * 4 + h) * 8 + kb) * 2048 + lane * 8;
; #pragma unroll
;               for (int q = 0; q < 4; ++q) kdA[q] = *(const bf16x8*)(kp + 512 * q); }
;             const int rbuf = step & 1, nbuf = rbuf ^ 1;
;             if (gc < 512) {
;                 u32x4 s0, s1;
;                 s0.x = pk2(S[0], S[1]); s0.y = pk2(S[2], S[3]); s0.z = pk2(S[4], S[5]); s0.w = pk2(S[6], S[7]);
;                 s1.x = pk2(S[8], S[9]); s1.y = pk2(S[10], S[11]); s1.z = pk2(S[12], S[13]); s1.w = pk2(S[14], S[15]);
;                 const bf16x8 sb0 = __builtin_bit_cast(bf16x8, s0), sb1 = __builtin_bit_cast(bf16x8, s1);
;                 f32x16 o0, o1;
; #pragma unroll
;                 for (int i = 0; i < 16; ++i) { o0[i] = 0.f; o1[i] = 0.f; }
;                 o0 = mfma32(qeA[0], sb0, o0); o0 = mfma32(qeA[1], sb1, o0);
;                 o1 = mfma32(qeA[2], sb0, o1); o1 = mfma32(qeA[3], sb1, o1);
;                 const int w3 = wave & 3;
;                 const bf16x8 vs = w3 == 0 ? vB[0] : (w3 == 1 ? vB[1] : (w3 == 2 ? vB[2] : vB[3]));
;                 if (wave < 4) o0 = mfma32(atA, vs, o0); else o1 = mfma32(atA, vs, o1);
;                 unsigned* rb = red + (size_t)(rbuf * 8 + wave) * 1024 + lane; unsigned* rbx = red + (size_t)(rbuf * 8 + wave) * 1024 + (lane ^ 32);
; #pragma unroll
;                 for (int i = 0; i < 8; ++i) { unsigned* w_ = (i & 1) ? rbx : rb; w_[i * 64] = pk2(o0[2 * i], o0[2 * i + 1]); w_[512 + i * 64] = pk2(o1[2 * i], o1[2 * i + 1]); }
;             }
;             SCAN_GSTORE(nbuf, gcur);
;             __syncthreads();
;             if (gc < 512) {
	s_waitcnt vmcnt(10)
	ds_write_b128 v239, v[204:207]
	v_cvt_pk_bf16_f32 v48, v0, v1
	v_cvt_pk_bf16_f32 v49, v2, v3
	v_cvt_pk_bf16_f32 v50, v4, v5
	v_cvt_pk_bf16_f32 v51, v6, v7
	v_cvt_pk_bf16_f32 v52, v8, v9
	v_cvt_pk_bf16_f32 v53, v10, v11
	v_cvt_pk_bf16_f32 v54, v12, v13
	v_cvt_pk_bf16_f32 v55, v14, v15
	v_mfma_f32_32x32x16_bf16 v[16:31], v[56:59], v[48:51], 0
	v_pk_mul_f32 v[0:1], v[162:163], v[0:1]
	v_pk_mul_f32 v[2:3], v[164:165], v[2:3]
	v_pk_mul_f32 v[4:5], v[166:167], v[4:5]
	v_mfma_f32_32x32x16_bf16 v[32:47], v[64:67], v[48:51], 0
	v_pk_mul_f32 v[6:7], v[168:169], v[6:7]
	v_pk_mul_f32 v[8:9], v[170:171], v[8:9]
	v_pk_mul_f32 v[10:11], v[172:173], v[10:11]
	v_mfma_f32_32x32x16_bf16 v[16:31], v[60:63], v[52:55], v[16:31]
	v_pk_mul_f32 v[12:13], v[174:175], v[12:13]
	v_pk_mul_f32 v[14:15], v[176:177], v[14:15]
	v_mfma_f32_32x32x16_bf16 v[32:47], v[68:71], v[52:55], v[32:47]
	v_mfma_f32_32x32x16_bf16 v[16:31], v[72:75], v[196:199], v[16:31]
	v_mfma_f32_32x32x16_bf16 v[0:15], v[76:79], v[128:131], v[0:15]
	v_mfma_f32_32x32x16_bf16 v[0:15], v[80:83], v[132:135], v[0:15]
	v_mfma_f32_32x32x16_bf16 v[0:15], v[84:87], v[136:139], v[0:15]
	v_mfma_f32_32x32x16_bf16 v[0:15], v[88:91], v[140:143], v[0:15]
	s_add_i32 s40, s30, 2
	s_min_u32 s40, s40, 0xff
	s_mul_i32 s40, s40, s29
	s_add_i32 s40, s40, s28
	s_lshl_b32 s41, s40, 17
	s_add_u32 s32, s20, s41
	s_addc_u32 s33, s21, 0
	s_add_u32 s34, s22, s41
	s_addc_u32 s35, s23, 0
	s_lshl_b32 s41, s40, 15
	s_add_u32 s36, s24, s41
	s_addc_u32 s37, s25, 0
	s_add_i32 s42, s30, s31
	s_min_u32 s42, s42, 0xff
	s_mul_i32 s42, s42, s29
	s_add_i32 s42, s42, s28
	v_mad_u64_u32 v[194:195], s[44:45], v238, s42, v[236:237]
	global_load_dwordx4 v[204:207], v[194:195], off
	global_load_dwordx4 v[76:79], v235, s[32:33]
	global_load_dwordx4 v[80:83], v235, s[32:33] offset:1024
	global_load_dwordx4 v[84:87], v235, s[32:33] offset:2048
	global_load_dwordx4 v[88:91], v235, s[32:33] offset:3072
	global_load_dwordx4 v[56:59], v232, s[34:35] offset:-4096
	global_load_dwordx4 v[60:63], v232, s[34:35]
	global_load_dwordx4 v[64:67], v233, s[34:35] offset:-4096
	global_load_dwordx4 v[68:71], v233, s[34:35]
	global_load_dwordx4 v[72:75], v251, s[36:37]
	ds_read_b128 v[144:147], v246 offset:4096
	ds_read_b128 v[148:151], v246 offset:5120
	ds_read_b128 v[152:155], v246 offset:6144
	ds_read_b128 v[156:159], v246 offset:7168
	ds_read_b128 v[200:203], v248 offset:4096
	ds_read_b128 v[178:181], v247 offset:1024
	ds_read_b128 v[182:185], v247 offset:1056
	ds_read_b128 v[186:189], v247 offset:1088
	ds_read_b128 v[190:193], v247 offset:1120
	v_cvt_pk_bf16_f32 v16, v16, v17
	v_cvt_pk_bf16_f32 v18, v18, v19
	v_cvt_pk_bf16_f32 v20, v20, v21
	v_cvt_pk_bf16_f32 v22, v22, v23
	v_cvt_pk_bf16_f32 v24, v24, v25
	v_cvt_pk_bf16_f32 v26, v26, v27
	v_cvt_pk_bf16_f32 v28, v28, v29
	v_cvt_pk_bf16_f32 v30, v30, v31
	ds_write2st64_b32 v241, v16, v20 offset0:0 offset1:2
	ds_write2st64_b32 v242, v18, v22 offset0:1 offset1:3
	ds_write2st64_b32 v241, v24, v28 offset0:4 offset1:6
	ds_write2st64_b32 v242, v26, v30 offset0:5 offset1:7
	v_cvt_pk_bf16_f32 v32, v32, v33
	v_cvt_pk_bf16_f32 v34, v34, v35
	v_cvt_pk_bf16_f32 v36, v36, v37
	v_cvt_pk_bf16_f32 v38, v38, v39
	v_cvt_pk_bf16_f32 v40, v40, v41
	v_cvt_pk_bf16_f32 v42, v42, v43
	v_cvt_pk_bf16_f32 v44, v44, v45
	v_cvt_pk_bf16_f32 v46, v46, v47
	ds_write2st64_b32 v243, v32, v36 offset0:0 offset1:2
	ds_write2st64_b32 v244, v34, v38 offset0:1 offset1:3
	ds_write2st64_b32 v243, v40, v44 offset0:4 offset1:6
	ds_write2st64_b32 v244, v42, v46 offset0:5 offset1:7
	s_waitcnt lgkmcnt(0)
	s_barrier
	s_mov_b32 s30, 1
	s_waitcnt vmcnt(10)
	ds_write_b128 v240, v[208:211]
	v_cvt_pk_bf16_f32 v48, v0, v1
	v_cvt_pk_bf16_f32 v49, v2, v3
	v_cvt_pk_bf16_f32 v50, v4, v5
	v_cvt_pk_bf16_f32 v51, v6, v7
	v_cvt_pk_bf16_f32 v52, v8, v9
	v_cvt_pk_bf16_f32 v53, v10, v11
	v_cvt_pk_bf16_f32 v54, v12, v13
	v_cvt_pk_bf16_f32 v55, v14, v15
	v_mfma_f32_32x32x16_bf16 v[16:31], v[92:95], v[48:51], 0
	v_pk_mul_f32 v[0:1], v[178:179], v[0:1]
	v_pk_mul_f32 v[2:3], v[180:181], v[2:3]
	v_pk_mul_f32 v[4:5], v[182:183], v[4:5]
	v_mfma_f32_32x32x16_bf16 v[32:47], v[100:103], v[48:51], 0
	v_pk_mul_f32 v[6:7], v[184:185], v[6:7]
	v_pk_mul_f32 v[8:9], v[186:187], v[8:9]
	v_pk_mul_f32 v[10:11], v[188:189], v[10:11]
	v_mfma_f32_32x32x16_bf16 v[16:31], v[96:99], v[52:55], v[16:31]
	v_pk_mul_f32 v[12:13], v[190:191], v[12:13]
	v_pk_mul_f32 v[14:15], v[192:193], v[14:15]
	v_mfma_f32_32x32x16_bf16 v[32:47], v[104:107], v[52:55], v[32:47]
	v_mfma_f32_32x32x16_bf16 v[16:31], v[108:111], v[200:203], v[16:31]
	v_mfma_f32_32x32x16_bf16 v[0:15], v[112:115], v[144:147], v[0:15]
	v_mfma_f32_32x32x16_bf16 v[0:15], v[116:119], v[148:151], v[0:15]
	v_mfma_f32_32x32x16_bf16 v[0:15], v[120:123], v[152:155], v[0:15]
	v_mfma_f32_32x32x16_bf16 v[0:15], v[124:127], v[156:159], v[0:15]
	s_add_i32 s40, s30, 2
	s_min_u32 s40, s40, 0xff
	s_mul_i32 s40, s40, s29
	s_add_i32 s40, s40, s28
	s_lshl_b32 s41, s40, 17
	s_add_u32 s32, s20, s41
	s_addc_u32 s33, s21, 0
	s_add_u32 s34, s22, s41
	s_addc_u32 s35, s23, 0
	s_lshl_b32 s41, s40, 15
	s_add_u32 s36, s24, s41
	s_addc_u32 s37, s25, 0
	s_add_i32 s42, s30, s31
	s_min_u32 s42, s42, 0xff
	s_mul_i32 s42, s42, s29
	s_add_i32 s42, s42, s28
	v_mad_u64_u32 v[194:195], s[44:45], v238, s42, v[236:237]
	global_load_dwordx4 v[208:211], v[194:195], off
	global_load_dwordx4 v[112:115], v235, s[32:33]
	global_load_dwordx4 v[116:119], v235, s[32:33] offset:1024
	global_load_dwordx4 v[120:123], v235, s[32:33] offset:2048
	global_load_dwordx4 v[124:127], v235, s[32:33] offset:3072
	global_load_dwordx4 v[92:95], v232, s[34:35] offset:-4096
	global_load_dwordx4 v[96:99], v232, s[34:35]
	global_load_dwordx4 v[100:103], v233, s[34:35] offset:-4096
	global_load_dwordx4 v[104:107], v233, s[34:35]
	global_load_dwordx4 v[108:111], v251, s[36:37]
	s_sub_i32 s40, s30, 1
	s_mul_i32 s40, s40, s29
	s_add_i32 s40, s40, s28
	s_lshl_b32 s40, s40, 18
	s_add_u32 s38, s26, s40
	s_addc_u32 s39, s27, 0
	ds_read2st64_b64 v[212:215], v245 offset0:0 offset1:8
	ds_read2st64_b64 v[216:219], v245 offset0:16 offset1:24
	ds_read2st64_b64 v[220:223], v245 offset0:32 offset1:40
	ds_read2st64_b64 v[224:227], v245 offset0:48 offset1:56
	ds_read_b128 v[128:131], v246 offset:0
	ds_read_b128 v[132:135], v246 offset:1024
	ds_read_b128 v[136:139], v246 offset:2048
	ds_read_b128 v[140:143], v246 offset:3072
	ds_read_b128 v[196:199], v248 offset:0
	ds_read_b128 v[162:165], v247 offset:0
	ds_read_b128 v[166:169], v247 offset:32
	ds_read_b128 v[170:173], v247 offset:64
	ds_read_b128 v[174:177], v247 offset:96
	s_waitcnt lgkmcnt(12)
; __device__ __forceinline__ void phase_scan(const Args& a, unsigned char* smem, int tid, int lane, int wave) {
;     ...
;         auto stepf = [&](const int step, unsigned& sc_issue, unsigned& sc_consume) __attribute__((always_inline)) {
;             const int nstep = step < 259 ? step + 1 : step, n2 = step < 258 ? step + 2 : 259;
;             SCAN_LOAD(nstep, nqe, nat);
;             SCAN_GLOAD(n2, gnxt);
;     ...
;             { int ss = step + SCOUT; ss = ss > 259 ? 259 : ss; const int gcs = SCAN_GC(ss); sc_issue = *(const unsigned*)(scb + (size_t)gcs * scsg); }
;     ...
;             const int gc = SCAN_GC(step); const size_t row0 = (size_t)gc * 64;
;             bf16x8 kdA[4];
;             { const bf16_t* kp = KDT + (((size_t)gc * 4 + h) * 8 + kb) * 2048 + lane * 8;
; #pragma unroll
;               for (int q = 0; q < 4; ++q) kdA[q] = *(const bf16x8*)(kp + 512 * q); }
;             const int rbuf = step & 1, nbuf = rbuf ^ 1;
;             if (gc < 512) {
;                 u32x4 s0, s1;
;                 s0.x = pk2(S[0], S[1]); s0.y = pk2(S[2], S[3]); s0.z = pk2(S[4], S[5]); s0.w = pk2(S[6], S[7]);
;                 s1.x = pk2(S[8], S[9]); s1.y = pk2(S[10], S[11]); s1.z = pk2(S[12], S[13]); s1.w = pk2(S[14], S[15]);
;                 const bf16x8 sb0 = __builtin_bit_cast(bf16x8, s0), sb1 = __builtin_bit_cast(bf16x8, s1);
;                 f32x16 o0, o1;
; #pragma unroll
;                 for (int i = 0; i < 16; ++i) { o0[i] = 0.f; o1[i] = 0.f; }
;                 o0 = mfma32(qeA[0], sb0, o0); o0 = mfma32(qeA[1], sb1, o0);
;                 o1 = mfma32(qeA[2], sb0, o1); o1 = mfma32(qeA[3], sb1, o1);
;                 const int w3 = wave & 3;
;                 const bf16x8 vs = w3 == 0 ? vB[0] : (w3 == 1 ? vB[1] : (w3 == 2 ? vB[2] : vB[3]));
;                 if (wave < 4) o0 = mfma32(atA, vs, o0); else o1 = mfma32(atA, vs, o1);
;                 unsigned* rb = red + (size_t)(rbuf * 8 + wave) * 1024 + lane; unsigned* rbx = red + (size_t)(rbuf * 8 + wave) * 1024 + (lane ^ 32);
; #pragma unroll
;                 for (int i = 0; i < 8; ++i) { unsigned* w_ = (i & 1) ? rbx : rb; w_[i * 64] = pk2(o0[2 * i], o0[2 * i + 1]); w_[512 + i * 64] = pk2(o1[2 * i], o1[2 * i + 1]); }
;             }
;             SCAN_GSTORE(nbuf, gcur);
;             __syncthreads();
;             if (gc < 512) {
	v_lshlrev_b32_e32 v229, 16, v213
	v_lshlrev_b32_e32 v228, 16, v212
	v_pk_add_f32 v[228:229], v[228:229], 0 op_sel_hi:[1,0]
	v_and_b32_e32 v231, 0xffff0000, v213
	v_and_b32_e32 v230, 0xffff0000, v212
	v_pk_add_f32 v[230:231], v[230:231], 0 op_sel_hi:[1,0]
	v_lshlrev_b32_e32 v195, 16, v215
	v_lshlrev_b32_e32 v194, 16, v214
	v_pk_add_f32 v[228:229], v[228:229], v[194:195]
	v_and_b32_e32 v215, 0xffff0000, v215
	v_and_b32_e32 v214, 0xffff0000, v214
	v_pk_add_f32 v[230:231], v[230:231], v[214:215]
	s_waitcnt lgkmcnt(11)
	v_lshlrev_b32_e32 v195, 16, v217
	v_lshlrev_b32_e32 v194, 16, v216
	v_pk_add_f32 v[228:229], v[228:229], v[194:195]
	v_and_b32_e32 v217, 0xffff0000, v217
	v_and_b32_e32 v216, 0xffff0000, v216
	v_pk_add_f32 v[230:231], v[230:231], v[216:217]
	v_lshlrev_b32_e32 v195, 16, v219
	v_lshlrev_b32_e32 v194, 16, v218
	v_pk_add_f32 v[228:229], v[228:229], v[194:195]
	v_and_b32_e32 v219, 0xffff0000, v219
	v_and_b32_e32 v218, 0xffff0000, v218
	v_pk_add_f32 v[230:231], v[230:231], v[218:219]
	s_waitcnt lgkmcnt(10)
	v_lshlrev_b32_e32 v195, 16, v221
	v_lshlrev_b32_e32 v194, 16, v220
	v_pk_add_f32 v[228:229], v[228:229], v[194:195]
	v_and_b32_e32 v221, 0xffff0000, v221
	v_and_b32_e32 v220, 0xffff0000, v220
	v_pk_add_f32 v[230:231], v[230:231], v[220:221]
	v_lshlrev_b32_e32 v195, 16, v223
	v_lshlrev_b32_e32 v194, 16, v222
	v_pk_add_f32 v[228:229], v[228:229], v[194:195]
	v_and_b32_e32 v223, 0xffff0000, v223
	v_and_b32_e32 v222, 0xffff0000, v222
	v_pk_add_f32 v[230:231], v[230:231], v[222:223]
	s_waitcnt lgkmcnt(9)
	v_lshlrev_b32_e32 v195, 16, v225
	v_lshlrev_b32_e32 v194, 16, v224
	v_pk_add_f32 v[228:229], v[228:229], v[194:195]
	v_and_b32_e32 v225, 0xffff0000, v225
	v_and_b32_e32 v224, 0xffff0000, v224
	v_pk_add_f32 v[230:231], v[230:231], v[224:225]
	v_lshlrev_b32_e32 v195, 16, v227
	v_lshlrev_b32_e32 v194, 16, v226
	v_pk_add_f32 v[228:229], v[228:229], v[194:195]
	v_and_b32_e32 v227, 0xffff0000, v227
	v_and_b32_e32 v226, 0xffff0000, v226
	v_pk_add_f32 v[230:231], v[230:231], v[226:227]
	v_cvt_pk_bf16_f32 v228, v228, v229
	v_cvt_pk_bf16_f32 v230, v230, v231
	global_store_dword v249, v228, s[38:39]
	global_store_dword v250, v230, s[38:39]
	v_cvt_pk_bf16_f32 v16, v16, v17
	v_cvt_pk_bf16_f32 v18, v18, v19
	v_cvt_pk_bf16_f32 v20, v20, v21
	v_cvt_pk_bf16_f32 v22, v22, v23
	v_cvt_pk_bf16_f32 v24, v24, v25
	v_cvt_pk_bf16_f32 v26, v26, v27
	v_cvt_pk_bf16_f32 v28, v28, v29
	v_cvt_pk_bf16_f32 v30, v30, v31
	ds_write2st64_b32 v241, v16, v20 offset0:128 offset1:130
	ds_write2st64_b32 v242, v18, v22 offset0:129 offset1:131
	ds_write2st64_b32 v241, v24, v28 offset0:132 offset1:134
	ds_write2st64_b32 v242, v26, v30 offset0:133 offset1:135
	v_cvt_pk_bf16_f32 v32, v32, v33
	v_cvt_pk_bf16_f32 v34, v34, v35
	v_cvt_pk_bf16_f32 v36, v36, v37
	v_cvt_pk_bf16_f32 v38, v38, v39
	v_cvt_pk_bf16_f32 v40, v40, v41
	v_cvt_pk_bf16_f32 v42, v42, v43
	v_cvt_pk_bf16_f32 v44, v44, v45
	v_cvt_pk_bf16_f32 v46, v46, v47
	ds_write2st64_b32 v243, v32, v36 offset0:128 offset1:130
	ds_write2st64_b32 v244, v34, v38 offset0:129 offset1:131
	ds_write2st64_b32 v243, v40, v44 offset0:132 offset1:134
	ds_write2st64_b32 v244, v42, v46 offset0:133 offset1:135
	s_waitcnt lgkmcnt(0)
	s_barrier
	s_mov_b32 s30, 2
	s_waitcnt vmcnt(12)
	ds_write_b128 v239, v[204:207]
	v_cvt_pk_bf16_f32 v48, v0, v1
	v_cvt_pk_bf16_f32 v49, v2, v3
	v_cvt_pk_bf16_f32 v50, v4, v5
	v_cvt_pk_bf16_f32 v51, v6, v7
	v_cvt_pk_bf16_f32 v52, v8, v9
	v_cvt_pk_bf16_f32 v53, v10, v11
	v_cvt_pk_bf16_f32 v54, v12, v13
	v_cvt_pk_bf16_f32 v55, v14, v15
	v_mfma_f32_32x32x16_bf16 v[16:31], v[56:59], v[48:51], 0
	v_pk_mul_f32 v[0:1], v[162:163], v[0:1]
	v_pk_mul_f32 v[2:3], v[164:165], v[2:3]
	v_pk_mul_f32 v[4:5], v[166:167], v[4:5]
	v_mfma_f32_32x32x16_bf16 v[32:47], v[64:67], v[48:51], 0
	v_pk_mul_f32 v[6:7], v[168:169], v[6:7]
	v_pk_mul_f32 v[8:9], v[170:171], v[8:9]
	v_pk_mul_f32 v[10:11], v[172:173], v[10:11]
	v_mfma_f32_32x32x16_bf16 v[16:31], v[60:63], v[52:55], v[16:31]
	v_pk_mul_f32 v[12:13], v[174:175], v[12:13]
	v_pk_mul_f32 v[14:15], v[176:177], v[14:15]
	v_mfma_f32_32x32x16_bf16 v[32:47], v[68:71], v[52:55], v[32:47]
	v_mfma_f32_32x32x16_bf16 v[16:31], v[72:75], v[196:199], v[16:31]
	v_mfma_f32_32x32x16_bf16 v[0:15], v[76:79], v[128:131], v[0:15]
	v_mfma_f32_32x32x16_bf16 v[0:15], v[80:83], v[132:135], v[0:15]
	v_mfma_f32_32x32x16_bf16 v[0:15], v[84:87], v[136:139], v[0:15]
	v_mfma_f32_32x32x16_bf16 v[0:15], v[88:91], v[140:143], v[0:15]
	s_add_i32 s40, s30, 2
	s_min_u32 s40, s40, 0xff
	s_mul_i32 s40, s40, s29
	s_add_i32 s40, s40, s28
	s_lshl_b32 s41, s40, 17
	s_add_u32 s32, s20, s41
	s_addc_u32 s33, s21, 0
	s_add_u32 s34, s22, s41
	s_addc_u32 s35, s23, 0
	s_lshl_b32 s41, s40, 15
	s_add_u32 s36, s24, s41
	s_addc_u32 s37, s25, 0
	s_add_i32 s42, s30, s31
	s_min_u32 s42, s42, 0xff
	s_mul_i32 s42, s42, s29
	s_add_i32 s42, s42, s28
	v_mad_u64_u32 v[194:195], s[44:45], v238, s42, v[236:237]
	global_load_dwordx4 v[204:207], v[194:195], off
	global_load_dwordx4 v[76:79], v235, s[32:33]
	global_load_dwordx4 v[80:83], v235, s[32:33] offset:1024
	global_load_dwordx4 v[84:87], v235, s[32:33] offset:2048
	global_load_dwordx4 v[88:91], v235, s[32:33] offset:3072
	global_load_dwordx4 v[56:59], v232, s[34:35] offset:-4096
	global_load_dwordx4 v[60:63], v232, s[34:35]
	global_load_dwordx4 v[64:67], v233, s[34:35] offset:-4096
	global_load_dwordx4 v[68:71], v233, s[34:35]
	global_load_dwordx4 v[72:75], v251, s[36:37]
	s_sub_i32 s40, s30, 1
	s_mul_i32 s40, s40, s29
	s_add_i32 s40, s40, s28
	s_lshl_b32 s40, s40, 18
	s_add_u32 s38, s26, s40
	s_addc_u32 s39, s27, 0
	ds_read2st64_b64 v[212:215], v245 offset0:64 offset1:72
	ds_read2st64_b64 v[216:219], v245 offset0:80 offset1:88
	ds_read2st64_b64 v[220:223], v245 offset0:96 offset1:104
	ds_read2st64_b64 v[224:227], v245 offset0:112 offset1:120
	ds_read_b128 v[144:147], v246 offset:4096
	ds_read_b128 v[148:151], v246 offset:5120
	ds_read_b128 v[152:155], v246 offset:6144
	ds_read_b128 v[156:159], v246 offset:7168
	ds_read_b128 v[200:203], v248 offset:4096
	ds_read_b128 v[178:181], v247 offset:1024
	ds_read_b128 v[182:185], v247 offset:1056
	ds_read_b128 v[186:189], v247 offset:1088
	ds_read_b128 v[190:193], v247 offset:1120
	s_waitcnt lgkmcnt(12)
; __device__ __forceinline__ void phase_scan(const Args& a, unsigned char* smem, int tid, int lane, int wave) {
;     ...
;         auto stepf = [&](const int step, unsigned& sc_issue, unsigned& sc_consume) __attribute__((always_inline)) {
;             const int nstep = step < 259 ? step + 1 : step, n2 = step < 258 ? step + 2 : 259;
;             SCAN_LOAD(nstep, nqe, nat);
;             SCAN_GLOAD(n2, gnxt);
;     ...
;             { int ss = step + SCOUT; ss = ss > 259 ? 259 : ss; const int gcs = SCAN_GC(ss); sc_issue = *(const unsigned*)(scb + (size_t)gcs * scsg); }
;     ...
;             const int gc = SCAN_GC(step); const size_t row0 = (size_t)gc * 64;
;             bf16x8 kdA[4];
;             { const bf16_t* kp = KDT + (((size_t)gc * 4 + h) * 8 + kb) * 2048 + lane * 8;
; #pragma unroll
;               for (int q = 0; q < 4; ++q) kdA[q] = *(const bf16x8*)(kp + 512 * q); }
;             const int rbuf = step & 1, nbuf = rbuf ^ 1;
;             if (gc < 512) {
;                 u32x4 s0, s1;
;                 s0.x = pk2(S[0], S[1]); s0.y = pk2(S[2], S[3]); s0.z = pk2(S[4], S[5]); s0.w = pk2(S[6], S[7]);
;                 s1.x = pk2(S[8], S[9]); s1.y = pk2(S[10], S[11]); s1.z = pk2(S[12], S[13]); s1.w = pk2(S[14], S[15]);
;                 const bf16x8 sb0 = __builtin_bit_cast(bf16x8, s0), sb1 = __builtin_bit_cast(bf16x8, s1);
;                 f32x16 o0, o1;
; #pragma unroll
;                 for (int i = 0; i < 16; ++i) { o0[i] = 0.f; o1[i] = 0.f; }
;                 o0 = mfma32(qeA[0], sb0, o0); o0 = mfma32(qeA[1], sb1, o0);
;                 o1 = mfma32(qeA[2], sb0, o1); o1 = mfma32(qeA[3], sb1, o1);
;                 const int w3 = wave & 3;
;                 const bf16x8 vs = w3 == 0 ? vB[0] : (w3 == 1 ? vB[1] : (w3 == 2 ? vB[2] : vB[3]));
;                 if (wave < 4) o0 = mfma32(atA, vs, o0); else o1 = mfma32(atA, vs, o1);
;                 unsigned* rb = red + (size_t)(rbuf * 8 + wave) * 1024 + lane; unsigned* rbx = red + (size_t)(rbuf * 8 + wave) * 1024 + (lane ^ 32);
; #pragma unroll
;                 for (int i = 0; i < 8; ++i) { unsigned* w_ = (i & 1) ? rbx : rb; w_[i * 64] = pk2(o0[2 * i], o0[2 * i + 1]); w_[512 + i * 64] = pk2(o1[2 * i], o1[2 * i + 1]); }
;             }
;             SCAN_GSTORE(nbuf, gcur);
;             __syncthreads();
;             if (gc < 512) {
	v_lshlrev_b32_e32 v229, 16, v213
	v_lshlrev_b32_e32 v228, 16, v212
	v_pk_add_f32 v[228:229], v[228:229], 0 op_sel_hi:[1,0]
	v_and_b32_e32 v231, 0xffff0000, v213
	v_and_b32_e32 v230, 0xffff0000, v212
	v_pk_add_f32 v[230:231], v[230:231], 0 op_sel_hi:[1,0]
	v_lshlrev_b32_e32 v195, 16, v215
	v_lshlrev_b32_e32 v194, 16, v214
	v_pk_add_f32 v[228:229], v[228:229], v[194:195]
	v_and_b32_e32 v215, 0xffff0000, v215
	v_and_b32_e32 v214, 0xffff0000, v214
	v_pk_add_f32 v[230:231], v[230:231], v[214:215]
	s_waitcnt lgkmcnt(11)
	v_lshlrev_b32_e32 v195, 16, v217
	v_lshlrev_b32_e32 v194, 16, v216
	v_pk_add_f32 v[228:229], v[228:229], v[194:195]
	v_and_b32_e32 v217, 0xffff0000, v217
	v_and_b32_e32 v216, 0xffff0000, v216
	v_pk_add_f32 v[230:231], v[230:231], v[216:217]
	v_lshlrev_b32_e32 v195, 16, v219
	v_lshlrev_b32_e32 v194, 16, v218
	v_pk_add_f32 v[228:229], v[228:229], v[194:195]
	v_and_b32_e32 v219, 0xffff0000, v219
	v_and_b32_e32 v218, 0xffff0000, v218
	v_pk_add_f32 v[230:231], v[230:231], v[218:219]
	s_waitcnt lgkmcnt(10)
	v_lshlrev_b32_e32 v195, 16, v221
	v_lshlrev_b32_e32 v194, 16, v220
	v_pk_add_f32 v[228:229], v[228:229], v[194:195]
	v_and_b32_e32 v221, 0xffff0000, v221
	v_and_b32_e32 v220, 0xffff0000, v220
	v_pk_add_f32 v[230:231], v[230:231], v[220:221]
	v_lshlrev_b32_e32 v195, 16, v223
	v_lshlrev_b32_e32 v194, 16, v222
	v_pk_add_f32 v[228:229], v[228:229], v[194:195]
	v_and_b32_e32 v223, 0xffff0000, v223
	v_and_b32_e32 v222, 0xffff0000, v222
	v_pk_add_f32 v[230:231], v[230:231], v[222:223]
	s_waitcnt lgkmcnt(9)
	v_lshlrev_b32_e32 v195, 16, v225
	v_lshlrev_b32_e32 v194, 16, v224
	v_pk_add_f32 v[228:229], v[228:229], v[194:195]
	v_and_b32_e32 v225, 0xffff0000, v225
	v_and_b32_e32 v224, 0xffff0000, v224
	v_pk_add_f32 v[230:231], v[230:231], v[224:225]
	v_lshlrev_b32_e32 v195, 16, v227
	v_lshlrev_b32_e32 v194, 16, v226
	v_pk_add_f32 v[228:229], v[228:229], v[194:195]
	v_and_b32_e32 v227, 0xffff0000, v227
	v_and_b32_e32 v226, 0xffff0000, v226
	v_pk_add_f32 v[230:231], v[230:231], v[226:227]
	v_cvt_pk_bf16_f32 v228, v228, v229
	v_cvt_pk_bf16_f32 v230, v230, v231
	global_store_dword v249, v228, s[38:39]
	global_store_dword v250, v230, s[38:39]
	v_cvt_pk_bf16_f32 v16, v16, v17
	v_cvt_pk_bf16_f32 v18, v18, v19
	v_cvt_pk_bf16_f32 v20, v20, v21
	v_cvt_pk_bf16_f32 v22, v22, v23
	v_cvt_pk_bf16_f32 v24, v24, v25
	v_cvt_pk_bf16_f32 v26, v26, v27
	v_cvt_pk_bf16_f32 v28, v28, v29
	v_cvt_pk_bf16_f32 v30, v30, v31
	ds_write2st64_b32 v241, v16, v20 offset0:0 offset1:2
	ds_write2st64_b32 v242, v18, v22 offset0:1 offset1:3
	ds_write2st64_b32 v241, v24, v28 offset0:4 offset1:6
	ds_write2st64_b32 v242, v26, v30 offset0:5 offset1:7
	v_cvt_pk_bf16_f32 v32, v32, v33
	v_cvt_pk_bf16_f32 v34, v34, v35
	v_cvt_pk_bf16_f32 v36, v36, v37
	v_cvt_pk_bf16_f32 v38, v38, v39
	v_cvt_pk_bf16_f32 v40, v40, v41
	v_cvt_pk_bf16_f32 v42, v42, v43
	v_cvt_pk_bf16_f32 v44, v44, v45
	v_cvt_pk_bf16_f32 v46, v46, v47
	ds_write2st64_b32 v243, v32, v36 offset0:0 offset1:2
	ds_write2st64_b32 v244, v34, v38 offset0:1 offset1:3
	ds_write2st64_b32 v243, v40, v44 offset0:4 offset1:6
	ds_write2st64_b32 v244, v42, v46 offset0:5 offset1:7
	s_waitcnt lgkmcnt(0)
	s_barrier
	s_mov_b32 s30, 3
	s_waitcnt vmcnt(14)
	ds_write_b128 v240, v[208:211]
	v_cvt_pk_bf16_f32 v48, v0, v1
	v_cvt_pk_bf16_f32 v49, v2, v3
	v_cvt_pk_bf16_f32 v50, v4, v5
	v_cvt_pk_bf16_f32 v51, v6, v7
	v_cvt_pk_bf16_f32 v52, v8, v9
	v_cvt_pk_bf16_f32 v53, v10, v11
	v_cvt_pk_bf16_f32 v54, v12, v13
	v_cvt_pk_bf16_f32 v55, v14, v15
	v_mfma_f32_32x32x16_bf16 v[16:31], v[92:95], v[48:51], 0
	v_pk_mul_f32 v[0:1], v[178:179], v[0:1]
	v_pk_mul_f32 v[2:3], v[180:181], v[2:3]
	v_pk_mul_f32 v[4:5], v[182:183], v[4:5]
	v_mfma_f32_32x32x16_bf16 v[32:47], v[100:103], v[48:51], 0
	v_pk_mul_f32 v[6:7], v[184:185], v[6:7]
	v_pk_mul_f32 v[8:9], v[186:187], v[8:9]
	v_pk_mul_f32 v[10:11], v[188:189], v[10:11]
	v_mfma_f32_32x32x16_bf16 v[16:31], v[96:99], v[52:55], v[16:31]
	v_pk_mul_f32 v[12:13], v[190:191], v[12:13]
	v_pk_mul_f32 v[14:15], v[192:193], v[14:15]
	v_mfma_f32_32x32x16_bf16 v[32:47], v[104:107], v[52:55], v[32:47]
	v_mfma_f32_32x32x16_bf16 v[16:31], v[108:111], v[200:203], v[16:31]
	v_mfma_f32_32x32x16_bf16 v[0:15], v[112:115], v[144:147], v[0:15]
	v_mfma_f32_32x32x16_bf16 v[0:15], v[116:119], v[148:151], v[0:15]
	v_mfma_f32_32x32x16_bf16 v[0:15], v[120:123], v[152:155], v[0:15]
	v_mfma_f32_32x32x16_bf16 v[0:15], v[124:127], v[156:159], v[0:15]
	s_add_i32 s40, s30, 2
	s_min_u32 s40, s40, 0xff
	s_mul_i32 s40, s40, s29
	s_add_i32 s40, s40, s28
	s_lshl_b32 s41, s40, 17
	s_add_u32 s32, s20, s41
	s_addc_u32 s33, s21, 0
	s_add_u32 s34, s22, s41
	s_addc_u32 s35, s23, 0
	s_lshl_b32 s41, s40, 15
	s_add_u32 s36, s24, s41
	s_addc_u32 s37, s25, 0
	s_add_i32 s42, s30, s31
	s_min_u32 s42, s42, 0xff
	s_mul_i32 s42, s42, s29
	s_add_i32 s42, s42, s28
	v_mad_u64_u32 v[194:195], s[44:45], v238, s42, v[236:237]
	global_load_dwordx4 v[208:211], v[194:195], off
	global_load_dwordx4 v[112:115], v235, s[32:33]
	global_load_dwordx4 v[116:119], v235, s[32:33] offset:1024
	global_load_dwordx4 v[120:123], v235, s[32:33] offset:2048
	global_load_dwordx4 v[124:127], v235, s[32:33] offset:3072
	global_load_dwordx4 v[92:95], v232, s[34:35] offset:-4096
	global_load_dwordx4 v[96:99], v232, s[34:35]
	global_load_dwordx4 v[100:103], v233, s[34:35] offset:-4096
	global_load_dwordx4 v[104:107], v233, s[34:35]
	global_load_dwordx4 v[108:111], v251, s[36:37]
	s_sub_i32 s40, s30, 1
	s_mul_i32 s40, s40, s29
	s_add_i32 s40, s40, s28
	s_lshl_b32 s40, s40, 18
	s_add_u32 s38, s26, s40
	s_addc_u32 s39, s27, 0
	ds_read2st64_b64 v[212:215], v245 offset0:0 offset1:8
	ds_read2st64_b64 v[216:219], v245 offset0:16 offset1:24
	ds_read2st64_b64 v[220:223], v245 offset0:32 offset1:40
	ds_read2st64_b64 v[224:227], v245 offset0:48 offset1:56
	ds_read_b128 v[128:131], v246 offset:0
	ds_read_b128 v[132:135], v246 offset:1024
	ds_read_b128 v[136:139], v246 offset:2048
	ds_read_b128 v[140:143], v246 offset:3072
	ds_read_b128 v[196:199], v248 offset:0
	ds_read_b128 v[162:165], v247 offset:0
	ds_read_b128 v[166:169], v247 offset:32
	ds_read_b128 v[170:173], v247 offset:64
	ds_read_b128 v[174:177], v247 offset:96
	s_waitcnt lgkmcnt(12)
; __device__ __forceinline__ void phase_scan(const Args& a, unsigned char* smem, int tid, int lane, int wave) {
;     ...
;         auto stepf = [&](const int step, unsigned& sc_issue, unsigned& sc_consume) __attribute__((always_inline)) {
;             const int nstep = step < 259 ? step + 1 : step, n2 = step < 258 ? step + 2 : 259;
;             SCAN_LOAD(nstep, nqe, nat);
;             SCAN_GLOAD(n2, gnxt);
;     ...
;             { int ss = step + SCOUT; ss = ss > 259 ? 259 : ss; const int gcs = SCAN_GC(ss); sc_issue = *(const unsigned*)(scb + (size_t)gcs * scsg); }
;     ...
;             const int gc = SCAN_GC(step); const size_t row0 = (size_t)gc * 64;
;             bf16x8 kdA[4];
;             { const bf16_t* kp = KDT + (((size_t)gc * 4 + h) * 8 + kb) * 2048 + lane * 8;
; #pragma unroll
;               for (int q = 0; q < 4; ++q) kdA[q] = *(const bf16x8*)(kp + 512 * q); }
;             const int rbuf = step & 1, nbuf = rbuf ^ 1;
;             if (gc < 512) {
;                 u32x4 s0, s1;
;                 s0.x = pk2(S[0], S[1]); s0.y = pk2(S[2], S[3]); s0.z = pk2(S[4], S[5]); s0.w = pk2(S[6], S[7]);
;                 s1.x = pk2(S[8], S[9]); s1.y = pk2(S[10], S[11]); s1.z = pk2(S[12], S[13]); s1.w = pk2(S[14], S[15]);
;                 const bf16x8 sb0 = __builtin_bit_cast(bf16x8, s0), sb1 = __builtin_bit_cast(bf16x8, s1);
;                 f32x16 o0, o1;
; #pragma unroll
;                 for (int i = 0; i < 16; ++i) { o0[i] = 0.f; o1[i] = 0.f; }
;                 o0 = mfma32(qeA[0], sb0, o0); o0 = mfma32(qeA[1], sb1, o0);
;                 o1 = mfma32(qeA[2], sb0, o1); o1 = mfma32(qeA[3], sb1, o1);
;                 const int w3 = wave & 3;
;                 const bf16x8 vs = w3 == 0 ? vB[0] : (w3 == 1 ? vB[1] : (w3 == 2 ? vB[2] : vB[3]));
;                 if (wave < 4) o0 = mfma32(atA, vs, o0); else o1 = mfma32(atA, vs, o1);
;                 unsigned* rb = red + (size_t)(rbuf * 8 + wave) * 1024 + lane; unsigned* rbx = red + (size_t)(rbuf * 8 + wave) * 1024 + (lane ^ 32);
; #pragma unroll
;                 for (int i = 0; i < 8; ++i) { unsigned* w_ = (i & 1) ? rbx : rb; w_[i * 64] = pk2(o0[2 * i], o0[2 * i + 1]); w_[512 + i * 64] = pk2(o1[2 * i], o1[2 * i + 1]); }
;             }
;             SCAN_GSTORE(nbuf, gcur);
;             __syncthreads();
;             if (gc < 512) {
	v_lshlrev_b32_e32 v229, 16, v213
	v_lshlrev_b32_e32 v228, 16, v212
	v_pk_add_f32 v[228:229], v[228:229], 0 op_sel_hi:[1,0]
	v_and_b32_e32 v231, 0xffff0000, v213
	v_and_b32_e32 v230, 0xffff0000, v212
	v_pk_add_f32 v[230:231], v[230:231], 0 op_sel_hi:[1,0]
	v_lshlrev_b32_e32 v195, 16, v215
	v_lshlrev_b32_e32 v194, 16, v214
	v_pk_add_f32 v[228:229], v[228:229], v[194:195]
	v_and_b32_e32 v215, 0xffff0000, v215
	v_and_b32_e32 v214, 0xffff0000, v214
	v_pk_add_f32 v[230:231], v[230:231], v[214:215]
	s_waitcnt lgkmcnt(11)
	v_lshlrev_b32_e32 v195, 16, v217
	v_lshlrev_b32_e32 v194, 16, v216
	v_pk_add_f32 v[228:229], v[228:229], v[194:195]
	v_and_b32_e32 v217, 0xffff0000, v217
	v_and_b32_e32 v216, 0xffff0000, v216
	v_pk_add_f32 v[230:231], v[230:231], v[216:217]
	v_lshlrev_b32_e32 v195, 16, v219
	v_lshlrev_b32_e32 v194, 16, v218
	v_pk_add_f32 v[228:229], v[228:229], v[194:195]
	v_and_b32_e32 v219, 0xffff0000, v219
	v_and_b32_e32 v218, 0xffff0000, v218
	v_pk_add_f32 v[230:231], v[230:231], v[218:219]
	s_waitcnt lgkmcnt(10)
	v_lshlrev_b32_e32 v195, 16, v221
	v_lshlrev_b32_e32 v194, 16, v220
	v_pk_add_f32 v[228:229], v[228:229], v[194:195]
	v_and_b32_e32 v221, 0xffff0000, v221
	v_and_b32_e32 v220, 0xffff0000, v220
	v_pk_add_f32 v[230:231], v[230:231], v[220:221]
	v_lshlrev_b32_e32 v195, 16, v223
	v_lshlrev_b32_e32 v194, 16, v222
	v_pk_add_f32 v[228:229], v[228:229], v[194:195]
	v_and_b32_e32 v223, 0xffff0000, v223
	v_and_b32_e32 v222, 0xffff0000, v222
	v_pk_add_f32 v[230:231], v[230:231], v[222:223]
	s_waitcnt lgkmcnt(9)
	v_lshlrev_b32_e32 v195, 16, v225
	v_lshlrev_b32_e32 v194, 16, v224
	v_pk_add_f32 v[228:229], v[228:229], v[194:195]
	v_and_b32_e32 v225, 0xffff0000, v225
	v_and_b32_e32 v224, 0xffff0000, v224
	v_pk_add_f32 v[230:231], v[230:231], v[224:225]
	v_lshlrev_b32_e32 v195, 16, v227
	v_lshlrev_b32_e32 v194, 16, v226
	v_pk_add_f32 v[228:229], v[228:229], v[194:195]
	v_and_b32_e32 v227, 0xffff0000, v227
	v_and_b32_e32 v226, 0xffff0000, v226
	v_pk_add_f32 v[230:231], v[230:231], v[226:227]
	v_cvt_pk_bf16_f32 v228, v228, v229
	v_cvt_pk_bf16_f32 v230, v230, v231
	global_store_dword v249, v228, s[38:39]
	global_store_dword v250, v230, s[38:39]
	v_cvt_pk_bf16_f32 v16, v16, v17
	v_cvt_pk_bf16_f32 v18, v18, v19
	v_cvt_pk_bf16_f32 v20, v20, v21
	v_cvt_pk_bf16_f32 v22, v22, v23
	v_cvt_pk_bf16_f32 v24, v24, v25
	v_cvt_pk_bf16_f32 v26, v26, v27
	v_cvt_pk_bf16_f32 v28, v28, v29
	v_cvt_pk_bf16_f32 v30, v30, v31
	ds_write2st64_b32 v241, v16, v20 offset0:128 offset1:130
	ds_write2st64_b32 v242, v18, v22 offset0:129 offset1:131
	ds_write2st64_b32 v241, v24, v28 offset0:132 offset1:134
	ds_write2st64_b32 v242, v26, v30 offset0:133 offset1:135
	v_cvt_pk_bf16_f32 v32, v32, v33
	v_cvt_pk_bf16_f32 v34, v34, v35
	v_cvt_pk_bf16_f32 v36, v36, v37
	v_cvt_pk_bf16_f32 v38, v38, v39
	v_cvt_pk_bf16_f32 v40, v40, v41
	v_cvt_pk_bf16_f32 v42, v42, v43
	v_cvt_pk_bf16_f32 v44, v44, v45
	v_cvt_pk_bf16_f32 v46, v46, v47
	ds_write2st64_b32 v243, v32, v36 offset0:128 offset1:130
	ds_write2st64_b32 v244, v34, v38 offset0:129 offset1:131
	ds_write2st64_b32 v243, v40, v44 offset0:132 offset1:134
	ds_write2st64_b32 v244, v42, v46 offset0:133 offset1:135
	s_waitcnt lgkmcnt(0)
	s_barrier
	s_mov_b32 s30, 4
.Lscan_loop:
	s_waitcnt vmcnt(14)
	ds_write_b128 v239, v[204:207]
	v_cvt_pk_bf16_f32 v48, v0, v1
	v_cvt_pk_bf16_f32 v49, v2, v3
	v_cvt_pk_bf16_f32 v50, v4, v5
	v_cvt_pk_bf16_f32 v51, v6, v7
	v_cvt_pk_bf16_f32 v52, v8, v9
	v_cvt_pk_bf16_f32 v53, v10, v11
	v_cvt_pk_bf16_f32 v54, v12, v13
	v_cvt_pk_bf16_f32 v55, v14, v15
	v_mfma_f32_32x32x16_bf16 v[16:31], v[56:59], v[48:51], 0
	v_pk_mul_f32 v[0:1], v[162:163], v[0:1]
	v_pk_mul_f32 v[2:3], v[164:165], v[2:3]
	v_pk_mul_f32 v[4:5], v[166:167], v[4:5]
	v_mfma_f32_32x32x16_bf16 v[32:47], v[64:67], v[48:51], 0
	v_pk_mul_f32 v[6:7], v[168:169], v[6:7]
	v_pk_mul_f32 v[8:9], v[170:171], v[8:9]
	v_pk_mul_f32 v[10:11], v[172:173], v[10:11]
	v_mfma_f32_32x32x16_bf16 v[16:31], v[60:63], v[52:55], v[16:31]
	v_pk_mul_f32 v[12:13], v[174:175], v[12:13]
	v_pk_mul_f32 v[14:15], v[176:177], v[14:15]
	v_mfma_f32_32x32x16_bf16 v[32:47], v[68:71], v[52:55], v[32:47]
	v_mfma_f32_32x32x16_bf16 v[16:31], v[72:75], v[196:199], v[16:31]
	v_mfma_f32_32x32x16_bf16 v[0:15], v[76:79], v[128:131], v[0:15]
	v_mfma_f32_32x32x16_bf16 v[0:15], v[80:83], v[132:135], v[0:15]
	v_mfma_f32_32x32x16_bf16 v[0:15], v[84:87], v[136:139], v[0:15]
	v_mfma_f32_32x32x16_bf16 v[0:15], v[88:91], v[140:143], v[0:15]
	s_add_i32 s40, s30, 2
	s_min_u32 s40, s40, 0xff
	s_mul_i32 s40, s40, s29
	s_add_i32 s40, s40, s28
	s_lshl_b32 s41, s40, 17
	s_add_u32 s32, s20, s41
	s_addc_u32 s33, s21, 0
	s_add_u32 s34, s22, s41
	s_addc_u32 s35, s23, 0
	s_lshl_b32 s41, s40, 15
	s_add_u32 s36, s24, s41
	s_addc_u32 s37, s25, 0
	s_add_i32 s42, s30, s31
	s_min_u32 s42, s42, 0xff
	s_mul_i32 s42, s42, s29
	s_add_i32 s42, s42, s28
	v_mad_u64_u32 v[194:195], s[44:45], v238, s42, v[236:237]
	global_load_dwordx4 v[204:207], v[194:195], off
	global_load_dwordx4 v[76:79], v235, s[32:33]
	global_load_dwordx4 v[80:83], v235, s[32:33] offset:1024
	global_load_dwordx4 v[84:87], v235, s[32:33] offset:2048
	global_load_dwordx4 v[88:91], v235, s[32:33] offset:3072
	global_load_dwordx4 v[56:59], v232, s[34:35] offset:-4096
	global_load_dwordx4 v[60:63], v232, s[34:35]
	global_load_dwordx4 v[64:67], v233, s[34:35] offset:-4096
	global_load_dwordx4 v[68:71], v233, s[34:35]
	global_load_dwordx4 v[72:75], v251, s[36:37]
	s_sub_i32 s40, s30, 1
	s_mul_i32 s40, s40, s29
	s_add_i32 s40, s40, s28
	s_lshl_b32 s40, s40, 18
	s_add_u32 s38, s26, s40
	s_addc_u32 s39, s27, 0
	ds_read2st64_b64 v[212:215], v245 offset0:64 offset1:72
	ds_read2st64_b64 v[216:219], v245 offset0:80 offset1:88
	ds_read2st64_b64 v[220:223], v245 offset0:96 offset1:104
	ds_read2st64_b64 v[224:227], v245 offset0:112 offset1:120
	ds_read_b128 v[144:147], v246 offset:4096
	ds_read_b128 v[148:151], v246 offset:5120
	ds_read_b128 v[152:155], v246 offset:6144
	ds_read_b128 v[156:159], v246 offset:7168
	ds_read_b128 v[200:203], v248 offset:4096
	ds_read_b128 v[178:181], v247 offset:1024
	ds_read_b128 v[182:185], v247 offset:1056
	ds_read_b128 v[186:189], v247 offset:1088
	ds_read_b128 v[190:193], v247 offset:1120
	s_waitcnt lgkmcnt(12)
; __device__ __forceinline__ void phase_scan(const Args& a, unsigned char* smem, int tid, int lane, int wave) {
;     ...
;         auto stepf = [&](const int step, unsigned& sc_issue, unsigned& sc_consume) __attribute__((always_inline)) {
;             const int nstep = step < 259 ? step + 1 : step, n2 = step < 258 ? step + 2 : 259;
;             SCAN_LOAD(nstep, nqe, nat);
;             SCAN_GLOAD(n2, gnxt);
;     ...
;             { int ss = step + SCOUT; ss = ss > 259 ? 259 : ss; const int gcs = SCAN_GC(ss); sc_issue = *(const unsigned*)(scb + (size_t)gcs * scsg); }
;     ...
;             const int gc = SCAN_GC(step); const size_t row0 = (size_t)gc * 64;
;             bf16x8 kdA[4];
;             { const bf16_t* kp = KDT + (((size_t)gc * 4 + h) * 8 + kb) * 2048 + lane * 8;
; #pragma unroll
;               for (int q = 0; q < 4; ++q) kdA[q] = *(const bf16x8*)(kp + 512 * q); }
;             const int rbuf = step & 1, nbuf = rbuf ^ 1;
;             if (gc < 512) {
;                 u32x4 s0, s1;
;                 s0.x = pk2(S[0], S[1]); s0.y = pk2(S[2], S[3]); s0.z = pk2(S[4], S[5]); s0.w = pk2(S[6], S[7]);
;                 s1.x = pk2(S[8], S[9]); s1.y = pk2(S[10], S[11]); s1.z = pk2(S[12], S[13]); s1.w = pk2(S[14], S[15]);
;                 const bf16x8 sb0 = __builtin_bit_cast(bf16x8, s0), sb1 = __builtin_bit_cast(bf16x8, s1);
;                 f32x16 o0, o1;
; #pragma unroll
;                 for (int i = 0; i < 16; ++i) { o0[i] = 0.f; o1[i] = 0.f; }
;                 o0 = mfma32(qeA[0], sb0, o0); o0 = mfma32(qeA[1], sb1, o0);
;                 o1 = mfma32(qeA[2], sb0, o1); o1 = mfma32(qeA[3], sb1, o1);
;                 const int w3 = wave & 3;
;                 const bf16x8 vs = w3 == 0 ? vB[0] : (w3 == 1 ? vB[1] : (w3 == 2 ? vB[2] : vB[3]));
;                 if (wave < 4) o0 = mfma32(atA, vs, o0); else o1 = mfma32(atA, vs, o1);
;                 unsigned* rb = red + (size_t)(rbuf * 8 + wave) * 1024 + lane; unsigned* rbx = red + (size_t)(rbuf * 8 + wave) * 1024 + (lane ^ 32);
; #pragma unroll
;                 for (int i = 0; i < 8; ++i) { unsigned* w_ = (i & 1) ? rbx : rb; w_[i * 64] = pk2(o0[2 * i], o0[2 * i + 1]); w_[512 + i * 64] = pk2(o1[2 * i], o1[2 * i + 1]); }
;             }
;             SCAN_GSTORE(nbuf, gcur);
;             __syncthreads();
;             if (gc < 512) {
	v_lshlrev_b32_e32 v229, 16, v213
	v_lshlrev_b32_e32 v228, 16, v212
	v_pk_add_f32 v[228:229], v[228:229], 0 op_sel_hi:[1,0]
	v_and_b32_e32 v231, 0xffff0000, v213
	v_and_b32_e32 v230, 0xffff0000, v212
	v_pk_add_f32 v[230:231], v[230:231], 0 op_sel_hi:[1,0]
	v_lshlrev_b32_e32 v195, 16, v215
	v_lshlrev_b32_e32 v194, 16, v214
	v_pk_add_f32 v[228:229], v[228:229], v[194:195]
	v_and_b32_e32 v215, 0xffff0000, v215
	v_and_b32_e32 v214, 0xffff0000, v214
	v_pk_add_f32 v[230:231], v[230:231], v[214:215]
	s_waitcnt lgkmcnt(11)
	v_lshlrev_b32_e32 v195, 16, v217
	v_lshlrev_b32_e32 v194, 16, v216
	v_pk_add_f32 v[228:229], v[228:229], v[194:195]
	v_and_b32_e32 v217, 0xffff0000, v217
	v_and_b32_e32 v216, 0xffff0000, v216
	v_pk_add_f32 v[230:231], v[230:231], v[216:217]
	v_lshlrev_b32_e32 v195, 16, v219
	v_lshlrev_b32_e32 v194, 16, v218
	v_pk_add_f32 v[228:229], v[228:229], v[194:195]
	v_and_b32_e32 v219, 0xffff0000, v219
	v_and_b32_e32 v218, 0xffff0000, v218
	v_pk_add_f32 v[230:231], v[230:231], v[218:219]
	s_waitcnt lgkmcnt(10)
	v_lshlrev_b32_e32 v195, 16, v221
	v_lshlrev_b32_e32 v194, 16, v220
	v_pk_add_f32 v[228:229], v[228:229], v[194:195]
	v_and_b32_e32 v221, 0xffff0000, v221
	v_and_b32_e32 v220, 0xffff0000, v220
	v_pk_add_f32 v[230:231], v[230:231], v[220:221]
	v_lshlrev_b32_e32 v195, 16, v223
	v_lshlrev_b32_e32 v194, 16, v222
	v_pk_add_f32 v[228:229], v[228:229], v[194:195]
	v_and_b32_e32 v223, 0xffff0000, v223
	v_and_b32_e32 v222, 0xffff0000, v222
	v_pk_add_f32 v[230:231], v[230:231], v[222:223]
	s_waitcnt lgkmcnt(9)
	v_lshlrev_b32_e32 v195, 16, v225
	v_lshlrev_b32_e32 v194, 16, v224
	v_pk_add_f32 v[228:229], v[228:229], v[194:195]
	v_and_b32_e32 v225, 0xffff0000, v225
	v_and_b32_e32 v224, 0xffff0000, v224
	v_pk_add_f32 v[230:231], v[230:231], v[224:225]
	v_lshlrev_b32_e32 v195, 16, v227
	v_lshlrev_b32_e32 v194, 16, v226
	v_pk_add_f32 v[228:229], v[228:229], v[194:195]
	v_and_b32_e32 v227, 0xffff0000, v227
	v_and_b32_e32 v226, 0xffff0000, v226
	v_pk_add_f32 v[230:231], v[230:231], v[226:227]
	v_cvt_pk_bf16_f32 v228, v228, v229
	v_cvt_pk_bf16_f32 v230, v230, v231
	global_store_dword v249, v228, s[38:39]
	global_store_dword v250, v230, s[38:39]
	v_cvt_pk_bf16_f32 v16, v16, v17
	v_cvt_pk_bf16_f32 v18, v18, v19
	v_cvt_pk_bf16_f32 v20, v20, v21
	v_cvt_pk_bf16_f32 v22, v22, v23
	v_cvt_pk_bf16_f32 v24, v24, v25
	v_cvt_pk_bf16_f32 v26, v26, v27
	v_cvt_pk_bf16_f32 v28, v28, v29
	v_cvt_pk_bf16_f32 v30, v30, v31
	ds_write2st64_b32 v241, v16, v20 offset0:0 offset1:2
	ds_write2st64_b32 v242, v18, v22 offset0:1 offset1:3
	ds_write2st64_b32 v241, v24, v28 offset0:4 offset1:6
	ds_write2st64_b32 v242, v26, v30 offset0:5 offset1:7
	v_cvt_pk_bf16_f32 v32, v32, v33
	v_cvt_pk_bf16_f32 v34, v34, v35
	v_cvt_pk_bf16_f32 v36, v36, v37
	v_cvt_pk_bf16_f32 v38, v38, v39
	v_cvt_pk_bf16_f32 v40, v40, v41
	v_cvt_pk_bf16_f32 v42, v42, v43
	v_cvt_pk_bf16_f32 v44, v44, v45
	v_cvt_pk_bf16_f32 v46, v46, v47
	ds_write2st64_b32 v243, v32, v36 offset0:0 offset1:2
	ds_write2st64_b32 v244, v34, v38 offset0:1 offset1:3
	ds_write2st64_b32 v243, v40, v44 offset0:4 offset1:6
	ds_write2st64_b32 v244, v42, v46 offset0:5 offset1:7
	s_waitcnt lgkmcnt(0)
	s_barrier
	s_add_i32 s30, s30, 1
	s_waitcnt vmcnt(14)
	ds_write_b128 v240, v[208:211]
	v_cvt_pk_bf16_f32 v48, v0, v1
	v_cvt_pk_bf16_f32 v49, v2, v3
	v_cvt_pk_bf16_f32 v50, v4, v5
	v_cvt_pk_bf16_f32 v51, v6, v7
	v_cvt_pk_bf16_f32 v52, v8, v9
	v_cvt_pk_bf16_f32 v53, v10, v11
	v_cvt_pk_bf16_f32 v54, v12, v13
	v_cvt_pk_bf16_f32 v55, v14, v15
	v_mfma_f32_32x32x16_bf16 v[16:31], v[92:95], v[48:51], 0
	v_pk_mul_f32 v[0:1], v[178:179], v[0:1]
	v_pk_mul_f32 v[2:3], v[180:181], v[2:3]
	v_pk_mul_f32 v[4:5], v[182:183], v[4:5]
	v_mfma_f32_32x32x16_bf16 v[32:47], v[100:103], v[48:51], 0
	v_pk_mul_f32 v[6:7], v[184:185], v[6:7]
	v_pk_mul_f32 v[8:9], v[186:187], v[8:9]
	v_pk_mul_f32 v[10:11], v[188:189], v[10:11]
	v_mfma_f32_32x32x16_bf16 v[16:31], v[96:99], v[52:55], v[16:31]
	v_pk_mul_f32 v[12:13], v[190:191], v[12:13]
	v_pk_mul_f32 v[14:15], v[192:193], v[14:15]
	v_mfma_f32_32x32x16_bf16 v[32:47], v[104:107], v[52:55], v[32:47]
	v_mfma_f32_32x32x16_bf16 v[16:31], v[108:111], v[200:203], v[16:31]
	v_mfma_f32_32x32x16_bf16 v[0:15], v[112:115], v[144:147], v[0:15]
	v_mfma_f32_32x32x16_bf16 v[0:15], v[116:119], v[148:151], v[0:15]
	v_mfma_f32_32x32x16_bf16 v[0:15], v[120:123], v[152:155], v[0:15]
	v_mfma_f32_32x32x16_bf16 v[0:15], v[124:127], v[156:159], v[0:15]
	s_add_i32 s40, s30, 2
	s_min_u32 s40, s40, 0xff
	s_mul_i32 s40, s40, s29
	s_add_i32 s40, s40, s28
	s_lshl_b32 s41, s40, 17
	s_add_u32 s32, s20, s41
	s_addc_u32 s33, s21, 0
	s_add_u32 s34, s22, s41
	s_addc_u32 s35, s23, 0
	s_lshl_b32 s41, s40, 15
	s_add_u32 s36, s24, s41
	s_addc_u32 s37, s25, 0
	s_add_i32 s42, s30, s31
	s_min_u32 s42, s42, 0xff
	s_mul_i32 s42, s42, s29
	s_add_i32 s42, s42, s28
	v_mad_u64_u32 v[194:195], s[44:45], v238, s42, v[236:237]
	global_load_dwordx4 v[208:211], v[194:195], off
	global_load_dwordx4 v[112:115], v235, s[32:33]
	global_load_dwordx4 v[116:119], v235, s[32:33] offset:1024
	global_load_dwordx4 v[120:123], v235, s[32:33] offset:2048
	global_load_dwordx4 v[124:127], v235, s[32:33] offset:3072
	global_load_dwordx4 v[92:95], v232, s[34:35] offset:-4096
	global_load_dwordx4 v[96:99], v232, s[34:35]
	global_load_dwordx4 v[100:103], v233, s[34:35] offset:-4096
	global_load_dwordx4 v[104:107], v233, s[34:35]
	global_load_dwordx4 v[108:111], v251, s[36:37]
	s_sub_i32 s40, s30, 1
	s_mul_i32 s40, s40, s29
	s_add_i32 s40, s40, s28
	s_lshl_b32 s40, s40, 18
	s_add_u32 s38, s26, s40
	s_addc_u32 s39, s27, 0
	ds_read2st64_b64 v[212:215], v245 offset0:0 offset1:8
	ds_read2st64_b64 v[216:219], v245 offset0:16 offset1:24
	ds_read2st64_b64 v[220:223], v245 offset0:32 offset1:40
	ds_read2st64_b64 v[224:227], v245 offset0:48 offset1:56
	ds_read_b128 v[128:131], v246 offset:0
	ds_read_b128 v[132:135], v246 offset:1024
	ds_read_b128 v[136:139], v246 offset:2048
	ds_read_b128 v[140:143], v246 offset:3072
	ds_read_b128 v[196:199], v248 offset:0
	ds_read_b128 v[162:165], v247 offset:0
	ds_read_b128 v[166:169], v247 offset:32
	ds_read_b128 v[170:173], v247 offset:64
	ds_read_b128 v[174:177], v247 offset:96
	s_waitcnt lgkmcnt(12)
; __device__ __forceinline__ unsigned pk2(float lo, float hi) { const f32x2 v = {lo, hi}; const bf16x2_t b = __builtin_convertvector(v, bf16x2_t); return __builtin_bit_cast(unsigned, b); }
; __device__ __forceinline__ f32x16 mfma32(bf16x8 a, bf16x8 b, f32x16 c) { return __builtin_amdgcn_mfma_f32_32x32x16_bf16(a, b, c, 0, 0, 0); }
; #define SCAN_LREAD(buf, VB_, DL_) do { _Pragma("unroll") for (int q_ = 0; q_ < 4; ++q_) { \
;         VB_[q_] = *(const bf16x8*)(vst + (((buf) * 4 + q_) * 64 + lane) * 16); \
;         DL_[q_] = *(const f32x4*)(dst + (buf) * 1024 + (kb * 32 + 8 * q_ + 4 * hh) * 4); } } while (0)
; __device__ __forceinline__ void phase_scan(const Args& a, unsigned char* smem, int tid, int lane, int wave) {
;     ...
;             if (gc < 512) {
;                 const int tp = tid >> 4, dv2 = (tid & 15) * 2, t = tp * 2, mt = t >> 5, tl = t & 31, pi = 2 * (tl >> 3) + ((tl & 3) >> 1), ln = ((tl >> 2) & 1) * 32 + dv2;
;                 const unsigned* rp = red + (size_t)rbuf * 8192 + (mt * 8 + pi) * 64 + (ln ^ ((pi & 1) << 5));
;                 float a0 = 0.f, a1 = 0.f, b0 = 0.f, b1 = 0.f;
; #pragma unroll
;                 for (int w = 0; w < 8; ++w) { const u32x2 v = *(const u32x2*)(rp + w * 1024); a0 += bflo(v.x); b0 += bfhi(v.x); a1 += bflo(v.y); b1 += bfhi(v.y); }
;                 bf16_t* op = O + (row0 + t) * 2048 + h * 512 + sl * 32 + dv2;
;                 *(unsigned*)op = pk2(a0, a1); *(unsigned*)(op + 2048) = pk2(b0, b1);
;             }
;             f32x4 ndl[4]; bf16x8 nvB[4];
;             SCAN_LREAD(nbuf, nvB, ndl);
; #pragma unroll
;             for (int i = 0; i < 16; ++i) S[i] *= dl[i >> 2][i & 3];
; #pragma unroll
;             for (int ks = 0; ks < 4; ++ks) S = mfma32(kdA[ks], vB[ks], S);
; #pragma unroll
;             for (int i = 0; i < 4; ++i) { vB[i] = nvB[i]; dl[i] = ndl[i]; qeA[i] = nqe[i]; }
;             atA = nat; gcur = gnxt;
;     ...
;             asm volatile("" :: "v"(sc_consume));
;     ...
;         };
; #pragma unroll 1
;         for (int step = 0; step < 260; step += 2) { stepf(step, scA, scB); stepf(step + 1, scB, scA); }
;         asm volatile("" :: "v"(scA), "v"(scB));
;         __syncthreads();
	v_lshlrev_b32_e32 v229, 16, v213
	v_lshlrev_b32_e32 v228, 16, v212
	v_pk_add_f32 v[228:229], v[228:229], 0 op_sel_hi:[1,0]
	v_and_b32_e32 v231, 0xffff0000, v213
	v_and_b32_e32 v230, 0xffff0000, v212
	v_pk_add_f32 v[230:231], v[230:231], 0 op_sel_hi:[1,0]
	v_lshlrev_b32_e32 v195, 16, v215
	v_lshlrev_b32_e32 v194, 16, v214
	v_pk_add_f32 v[228:229], v[228:229], v[194:195]
	v_and_b32_e32 v215, 0xffff0000, v215
	v_and_b32_e32 v214, 0xffff0000, v214
	v_pk_add_f32 v[230:231], v[230:231], v[214:215]
	s_waitcnt lgkmcnt(11)
	v_lshlrev_b32_e32 v195, 16, v217
	v_lshlrev_b32_e32 v194, 16, v216
	v_pk_add_f32 v[228:229], v[228:229], v[194:195]
	v_and_b32_e32 v217, 0xffff0000, v217
	v_and_b32_e32 v216, 0xffff0000, v216
	v_pk_add_f32 v[230:231], v[230:231], v[216:217]
	v_lshlrev_b32_e32 v195, 16, v219
	v_lshlrev_b32_e32 v194, 16, v218
	v_pk_add_f32 v[228:229], v[228:229], v[194:195]
	v_and_b32_e32 v219, 0xffff0000, v219
	v_and_b32_e32 v218, 0xffff0000, v218
	v_pk_add_f32 v[230:231], v[230:231], v[218:219]
	s_waitcnt lgkmcnt(10)
	v_lshlrev_b32_e32 v195, 16, v221
	v_lshlrev_b32_e32 v194, 16, v220
	v_pk_add_f32 v[228:229], v[228:229], v[194:195]
	v_and_b32_e32 v221, 0xffff0000, v221
	v_and_b32_e32 v220, 0xffff0000, v220
	v_pk_add_f32 v[230:231], v[230:231], v[220:221]
	v_lshlrev_b32_e32 v195, 16, v223
	v_lshlrev_b32_e32 v194, 16, v222
	v_pk_add_f32 v[228:229], v[228:229], v[194:195]
	v_and_b32_e32 v223, 0xffff0000, v223
	v_and_b32_e32 v222, 0xffff0000, v222
	v_pk_add_f32 v[230:231], v[230:231], v[222:223]
	s_waitcnt lgkmcnt(9)
	v_lshlrev_b32_e32 v195, 16, v225
	v_lshlrev_b32_e32 v194, 16, v224
	v_pk_add_f32 v[228:229], v[228:229], v[194:195]
	v_and_b32_e32 v225, 0xffff0000, v225
	v_and_b32_e32 v224, 0xffff0000, v224
	v_pk_add_f32 v[230:231], v[230:231], v[224:225]
	v_lshlrev_b32_e32 v195, 16, v227
	v_lshlrev_b32_e32 v194, 16, v226
	v_pk_add_f32 v[228:229], v[228:229], v[194:195]
	v_and_b32_e32 v227, 0xffff0000, v227
	v_and_b32_e32 v226, 0xffff0000, v226
	v_pk_add_f32 v[230:231], v[230:231], v[226:227]
	v_cvt_pk_bf16_f32 v228, v228, v229
	v_cvt_pk_bf16_f32 v230, v230, v231
	global_store_dword v249, v228, s[38:39]
	global_store_dword v250, v230, s[38:39]
	v_cvt_pk_bf16_f32 v16, v16, v17
	v_cvt_pk_bf16_f32 v18, v18, v19
	v_cvt_pk_bf16_f32 v20, v20, v21
	v_cvt_pk_bf16_f32 v22, v22, v23
	v_cvt_pk_bf16_f32 v24, v24, v25
	v_cvt_pk_bf16_f32 v26, v26, v27
	v_cvt_pk_bf16_f32 v28, v28, v29
	v_cvt_pk_bf16_f32 v30, v30, v31
	ds_write2st64_b32 v241, v16, v20 offset0:128 offset1:130
	ds_write2st64_b32 v242, v18, v22 offset0:129 offset1:131
	ds_write2st64_b32 v241, v24, v28 offset0:132 offset1:134
	ds_write2st64_b32 v242, v26, v30 offset0:133 offset1:135
	v_cvt_pk_bf16_f32 v32, v32, v33
	v_cvt_pk_bf16_f32 v34, v34, v35
	v_cvt_pk_bf16_f32 v36, v36, v37
	v_cvt_pk_bf16_f32 v38, v38, v39
	v_cvt_pk_bf16_f32 v40, v40, v41
	v_cvt_pk_bf16_f32 v42, v42, v43
	v_cvt_pk_bf16_f32 v44, v44, v45
	v_cvt_pk_bf16_f32 v46, v46, v47
	ds_write2st64_b32 v243, v32, v36 offset0:128 offset1:130
	ds_write2st64_b32 v244, v34, v38 offset0:129 offset1:131
	ds_write2st64_b32 v243, v40, v44 offset0:132 offset1:134
	ds_write2st64_b32 v244, v42, v46 offset0:133 offset1:135
	s_waitcnt lgkmcnt(0)
	s_barrier
	s_add_i32 s30, s30, 1
	s_cmp_lt_u32 s30, 256
	s_cbranch_scc1 .Lscan_loop
	s_sub_i32 s40, s30, 1
	s_mul_i32 s40, s40, s29
	s_add_i32 s40, s40, s28
	s_lshl_b32 s40, s40, 18
	s_add_u32 s38, s26, s40
	s_addc_u32 s39, s27, 0
	ds_read2st64_b64 v[212:215], v245 offset0:64 offset1:72
	ds_read2st64_b64 v[216:219], v245 offset0:80 offset1:88
	ds_read2st64_b64 v[220:223], v245 offset0:96 offset1:104
	ds_read2st64_b64 v[224:227], v245 offset0:112 offset1:120
	s_waitcnt lgkmcnt(3)
	v_lshlrev_b32_e32 v229, 16, v213
	v_lshlrev_b32_e32 v228, 16, v212
	v_pk_add_f32 v[228:229], v[228:229], 0 op_sel_hi:[1,0]
	v_and_b32_e32 v231, 0xffff0000, v213
	v_and_b32_e32 v230, 0xffff0000, v212
	v_pk_add_f32 v[230:231], v[230:231], 0 op_sel_hi:[1,0]
	v_lshlrev_b32_e32 v195, 16, v215
	v_lshlrev_b32_e32 v194, 16, v214
	v_pk_add_f32 v[228:229], v[228:229], v[194:195]
	v_and_b32_e32 v215, 0xffff0000, v215
	v_and_b32_e32 v214, 0xffff0000, v214
	v_pk_add_f32 v[230:231], v[230:231], v[214:215]
	s_waitcnt lgkmcnt(2)
	v_lshlrev_b32_e32 v195, 16, v217
	v_lshlrev_b32_e32 v194, 16, v216
	v_pk_add_f32 v[228:229], v[228:229], v[194:195]
	v_and_b32_e32 v217, 0xffff0000, v217
	v_and_b32_e32 v216, 0xffff0000, v216
	v_pk_add_f32 v[230:231], v[230:231], v[216:217]
	v_lshlrev_b32_e32 v195, 16, v219
	v_lshlrev_b32_e32 v194, 16, v218
	v_pk_add_f32 v[228:229], v[228:229], v[194:195]
	v_and_b32_e32 v219, 0xffff0000, v219
	v_and_b32_e32 v218, 0xffff0000, v218
	v_pk_add_f32 v[230:231], v[230:231], v[218:219]
	s_waitcnt lgkmcnt(1)
	v_lshlrev_b32_e32 v195, 16, v221
	v_lshlrev_b32_e32 v194, 16, v220
	v_pk_add_f32 v[228:229], v[228:229], v[194:195]
	v_and_b32_e32 v221, 0xffff0000, v221
	v_and_b32_e32 v220, 0xffff0000, v220
	v_pk_add_f32 v[230:231], v[230:231], v[220:221]
	v_lshlrev_b32_e32 v195, 16, v223
	v_lshlrev_b32_e32 v194, 16, v222
	v_pk_add_f32 v[228:229], v[228:229], v[194:195]
	v_and_b32_e32 v223, 0xffff0000, v223
	v_and_b32_e32 v222, 0xffff0000, v222
	v_pk_add_f32 v[230:231], v[230:231], v[222:223]
	s_waitcnt lgkmcnt(0)
	v_lshlrev_b32_e32 v195, 16, v225
	v_lshlrev_b32_e32 v194, 16, v224
	v_pk_add_f32 v[228:229], v[228:229], v[194:195]
	v_and_b32_e32 v225, 0xffff0000, v225
	v_and_b32_e32 v224, 0xffff0000, v224
	v_pk_add_f32 v[230:231], v[230:231], v[224:225]
	v_lshlrev_b32_e32 v195, 16, v227
	v_lshlrev_b32_e32 v194, 16, v226
	v_pk_add_f32 v[228:229], v[228:229], v[194:195]
	v_and_b32_e32 v227, 0xffff0000, v227
	v_and_b32_e32 v226, 0xffff0000, v226
	v_pk_add_f32 v[230:231], v[230:231], v[226:227]
	v_cvt_pk_bf16_f32 v228, v228, v229
	v_cvt_pk_bf16_f32 v230, v230, v231
	global_store_dword v249, v228, s[38:39]
	global_store_dword v250, v230, s[38:39]
	s_waitcnt vmcnt(0) lgkmcnt(0)
	s_barrier
	v_readlane_b32 s50, v252, 0
	v_readlane_b32 s51, v252, 1
	s_nop 3
	s_load_dword s40, s[50:51], 0x98
	s_waitcnt lgkmcnt(0)
	s_add_i32 s14, s14, s40
	s_cmpk_lt_i32 s14, 0x100
	s_cbranch_scc1 .Lscan_unit
